# priority kept raised through the whole fast-path iteration (no drop after QK or after PV)
# baseline (speedup 1.0000x reference)
; template <int MODE, int DK, bool PASS2> ...
;     ...
;             if (active) {
;                 f32x16 s0, s1;
;                 if (MODE == M_FOX) {
;                     const LAS float* ct = (const LAS float*)(lds + F_CT + buf * 256) + 8 * g;
; #pragma unroll
;                     for (int q4 = 0; q4 < 4; ++q4) {
;                         const f32x4 a = *(const LAS f32x4*)(ct + (q4 >> 1) * 16 + (q4 & 1) * 4), b = *(const LAS f32x4*)(ct + 32 + (q4 >> 1) * 16 + (q4 & 1) * 4);
; #pragma unroll
;                         for (int e = 0; e < 4; ++e) { s0[q4 * 4 + e] = a[e]; s1[q4 * 4 + e] = b[e]; }
;                     }
;                 } else { s0 = (f32x16)(0.f); s1 = (f32x16)(0.f); }
;                 const LAS unsigned char* kb = lds + F_KB0 + buf * F_KBS + g * 16 + prow * KSTR;
;                 __builtin_amdgcn_s_setprio(1);
; #pragma unroll
;                 for (int kk = 0; kk < DK / 16; ++kk) {
;                     const bf16x8 a0 = *(const LAS bf16x8*)(kb + kk * 32);
;                     const bf16x8 a1 = *(const LAS bf16x8*)(kb + 32 * KSTR + kk * 32);
;                     s0 = mfma32(a0, qf[kk], s0); s1 = mfma32(a1, qf[kk], s1);
;                 }
;                 __builtin_amdgcn_s_setprio(0);
;                 const bool need_causal = pos_max > t_wmin;
;                 const bool need_bias = (MODE != M_FOX) && ((t_wmin - pos_max) < 128);
;                 const bool need_win = (MODE == M_WIN) && (t_wmax - pos_min >= 512);
;                 if (!PASS2 && !(need_causal || need_bias || need_win)) {
;                     float mx = fmaxf(s0[0], s1[0]);
; #pragma unroll
;                     for (int r = 1; r < 16; ++r) mx = fmax3(mx, s0[r], s1[r]);
;                     if (MODE == M_SLC) mx = selbit ? mx : NEG;
;                     mx = xhalf_max(mx);
;                     const float mxs = mx * sl2;
;                     const float mn = (mxs > m_run + 8.0f) ? mxs : m_run;
;                     const float alpha = fexp2(m_run - mn);
;                     m_run = mn;
;                     float nm = -mn;
;                     if (MODE == M_SLC) nm = selbit ? nm : -__builtin_inff();
;                     float ps0 = 0.f, ps1 = 0.f;
; #pragma unroll
;                     for (int r = 0; r < 16; ++r) {
;                         s0[r] = fexp2(__builtin_fmaf(s0[r], sl2, nm)); s1[r] = fexp2(__builtin_fmaf(s1[r], sl2, nm));
.LBB0_942:
	s_sub_i32 s24, s87, 63
	v_cmp_le_i32_e32 vcc, s24, v227
	v_mov_b32_e32 v2, 0
	s_and_saveexec_b64 s[50:51], vcc
	s_cbranch_execz .LBB0_954
	v_lshl_add_u32 v2, s86, 8, v229
	ds_read_b128 v[98:101], v2
	ds_read_b128 v[102:105], v2 offset:16
	ds_read_b128 v[82:85], v2 offset:128
	ds_read_b128 v[86:89], v2 offset:144
	ds_read_b128 v[106:109], v2 offset:64
	ds_read_b128 v[110:113], v2 offset:80
	ds_read_b128 v[90:93], v2 offset:192
	ds_read_b128 v[94:97], v2 offset:208
	s_mul_i32 s24, s86, 0x4400
	v_add_u32_e32 v2, s24, v230
	s_setprio 1
	ds_read_b128 v[4:7], v2
	ds_read_b128 v[8:11], v2 offset:32
	s_waitcnt lgkmcnt(1)
	v_mfma_f32_32x32x16_bf16 v[98:113], v[4:7], v[146:149], v[98:113]
	ds_read_b128 v[4:7], v2 offset:8704
	ds_read_b128 v[12:15], v2 offset:8736
	s_waitcnt lgkmcnt(1)
	v_mfma_f32_32x32x16_bf16 v[82:97], v[4:7], v[146:149], v[82:97]
	v_mfma_f32_32x32x16_bf16 v[98:113], v[8:11], v[150:153], v[98:113]
	ds_read_b128 v[4:7], v2 offset:64
	ds_read_b128 v[8:11], v2 offset:96
	s_waitcnt lgkmcnt(2)
	v_mfma_f32_32x32x16_bf16 v[82:97], v[12:15], v[150:153], v[82:97]
	s_waitcnt lgkmcnt(1)
	v_mfma_f32_32x32x16_bf16 v[98:113], v[4:7], v[154:157], v[98:113]
	ds_read_b128 v[4:7], v2 offset:8768
	ds_read_b128 v[12:15], v2 offset:8800
	s_waitcnt lgkmcnt(1)
	v_mfma_f32_32x32x16_bf16 v[82:97], v[4:7], v[154:157], v[82:97]
	v_mfma_f32_32x32x16_bf16 v[98:113], v[8:11], v[158:161], v[98:113]
	ds_read_b128 v[4:7], v2 offset:128
	ds_read_b128 v[8:11], v2 offset:160
	s_waitcnt lgkmcnt(2)
	v_mfma_f32_32x32x16_bf16 v[82:97], v[12:15], v[158:161], v[82:97]
	s_waitcnt lgkmcnt(1)
	v_mfma_f32_32x32x16_bf16 v[98:113], v[4:7], v[162:165], v[98:113]
	ds_read_b128 v[4:7], v2 offset:8832
	ds_read_b128 v[12:15], v2 offset:8864
	s_waitcnt lgkmcnt(1)
	v_mfma_f32_32x32x16_bf16 v[82:97], v[4:7], v[162:165], v[82:97]
	v_mfma_f32_32x32x16_bf16 v[98:113], v[8:11], v[166:169], v[98:113]
	ds_read_b128 v[4:7], v2 offset:192
	ds_read_b128 v[8:11], v2 offset:224
	s_waitcnt lgkmcnt(2)
	v_mfma_f32_32x32x16_bf16 v[82:97], v[12:15], v[166:169], v[82:97]
	s_waitcnt lgkmcnt(1)
	v_mfma_f32_32x32x16_bf16 v[98:113], v[4:7], v[170:173], v[98:113]
	ds_read_b128 v[4:7], v2 offset:8896
	ds_read_b128 v[12:15], v2 offset:8928
	s_waitcnt lgkmcnt(1)
	v_mfma_f32_32x32x16_bf16 v[82:97], v[4:7], v[170:173], v[82:97]
	v_mfma_f32_32x32x16_bf16 v[98:113], v[8:11], v[174:177], v[98:113]
	s_waitcnt lgkmcnt(0)
	v_mfma_f32_32x32x16_bf16 v[82:97], v[12:15], v[174:177], v[82:97]
	s_nop 0
	v_cmp_le_i32_e32 vcc, s87, v216
	v_add_f32_e32 v2, 0x41000000, v239
	s_and_saveexec_b64 s[52:53], vcc
	s_xor_b64 s[52:53], exec, s[52:53]
	s_cbranch_execz .LBB0_947
	s_cmp_eq_u64 s[52:53], 0
	s_cbranch_scc1 .Lfast_fox
	s_nop 3
	v_max_f32_e32 v4, v98, v98
	s_nop 0
	v_max_f32_e32 v5, v82, v82
	v_max_f32_e32 v4, v4, v5
	v_max3_f32 v4, v4, v99, v83
	s_nop 0
	v_max3_f32 v4, v4, v100, v84
	s_nop 0
	v_max3_f32 v4, v4, v101, v85
	s_nop 0
	v_max3_f32 v4, v4, v102, v86
	s_nop 0
	v_max3_f32 v4, v4, v103, v87
	s_nop 0
	v_max3_f32 v4, v4, v104, v88
	s_nop 0
	v_max3_f32 v4, v4, v105, v89
	s_nop 0
	v_max3_f32 v4, v4, v106, v90
	s_nop 0
	v_max3_f32 v4, v4, v107, v91
	s_nop 0
	v_max3_f32 v4, v4, v108, v92
	s_nop 0
	v_max3_f32 v4, v4, v109, v93
	s_nop 0
	v_max3_f32 v4, v4, v110, v94
	s_nop 0
	v_max3_f32 v4, v4, v111, v95
	s_nop 0
	v_max3_f32 v4, v4, v112, v96
	s_nop 0
	v_max3_f32 v4, v4, v113, v97
	s_nop 0
	v_mov_b32_e32 v5, v4
	s_nop 1
	v_permlane32_swap_b32_e32 v4, v5
	v_max_f32_e32 v5, v5, v5
	v_max_f32_e32 v4, v4, v4
	v_max_f32_e32 v4, v4, v5
	v_mul_f32_e32 v4, 0x3e0293ee, v4
	v_cmp_gt_f32_e32 vcc, v4, v2
	s_nop 1
	v_cndmask_b32_e32 v4, v239, v4, vcc
	v_sub_f32_e32 v2, v239, v4
	v_exp_f32_e32 v2, v2
	s_nop 0
	v_cmp_neq_f32_e32 vcc, 1.0, v2
	s_cbranch_vccz .LBB0_946
	v_pk_mul_f32 v[80:81], v[80:81], v[2:3] op_sel_hi:[1,0]
	v_pk_mul_f32 v[78:79], v[78:79], v[2:3] op_sel_hi:[1,0]
	v_pk_mul_f32 v[76:77], v[76:77], v[2:3] op_sel_hi:[1,0]
	v_pk_mul_f32 v[74:75], v[74:75], v[2:3] op_sel_hi:[1,0]
	v_pk_mul_f32 v[72:73], v[72:73], v[2:3] op_sel_hi:[1,0]
	v_pk_mul_f32 v[70:71], v[70:71], v[2:3] op_sel_hi:[1,0]
	v_pk_mul_f32 v[68:69], v[68:69], v[2:3] op_sel_hi:[1,0]
	v_pk_mul_f32 v[66:67], v[66:67], v[2:3] op_sel_hi:[1,0]
	v_pk_mul_f32 v[64:65], v[64:65], v[2:3] op_sel_hi:[1,0]
	v_pk_mul_f32 v[62:63], v[62:63], v[2:3] op_sel_hi:[1,0]
	v_pk_mul_f32 v[60:61], v[60:61], v[2:3] op_sel_hi:[1,0]
	v_pk_mul_f32 v[58:59], v[58:59], v[2:3] op_sel_hi:[1,0]
	v_pk_mul_f32 v[56:57], v[56:57], v[2:3] op_sel_hi:[1,0]
	v_pk_mul_f32 v[54:55], v[54:55], v[2:3] op_sel_hi:[1,0]
	v_pk_mul_f32 v[52:53], v[52:53], v[2:3] op_sel_hi:[1,0]
	v_pk_mul_f32 v[50:51], v[50:51], v[2:3] op_sel_hi:[1,0]
	v_pk_mul_f32 v[48:49], v[48:49], v[2:3] op_sel_hi:[1,0]
	v_pk_mul_f32 v[46:47], v[46:47], v[2:3] op_sel_hi:[1,0]
	v_pk_mul_f32 v[44:45], v[44:45], v[2:3] op_sel_hi:[1,0]
	v_pk_mul_f32 v[42:43], v[42:43], v[2:3] op_sel_hi:[1,0]
	v_pk_mul_f32 v[40:41], v[40:41], v[2:3] op_sel_hi:[1,0]
	v_pk_mul_f32 v[38:39], v[38:39], v[2:3] op_sel_hi:[1,0]
	v_pk_mul_f32 v[36:37], v[36:37], v[2:3] op_sel_hi:[1,0]
	v_pk_mul_f32 v[34:35], v[34:35], v[2:3] op_sel_hi:[1,0]
	v_pk_mul_f32 v[32:33], v[32:33], v[2:3] op_sel_hi:[1,0]
	v_pk_mul_f32 v[30:31], v[30:31], v[2:3] op_sel_hi:[1,0]
	v_pk_mul_f32 v[28:29], v[28:29], v[2:3] op_sel_hi:[1,0]
	v_pk_mul_f32 v[26:27], v[26:27], v[2:3] op_sel_hi:[1,0]
	v_pk_mul_f32 v[24:25], v[24:25], v[2:3] op_sel_hi:[1,0]
	v_pk_mul_f32 v[22:23], v[22:23], v[2:3] op_sel_hi:[1,0]
	v_pk_mul_f32 v[20:21], v[20:21], v[2:3] op_sel_hi:[1,0]
	v_pk_mul_f32 v[18:19], v[18:19], v[2:3] op_sel_hi:[1,0]

; template <int MODE, int DK, bool PASS2> ...
;     ...
;                     float ps0 = 0.f, ps1 = 0.f;
; #pragma unroll
;                     for (int r = 0; r < 16; ++r) {
;                         s0[r] = fexp2(__builtin_fmaf(s0[r], sl2, nm)); s1[r] = fexp2(__builtin_fmaf(s1[r], sl2, nm));
;                         ps0 += s0[r]; ps1 += s1[r];
;                     }
;                     l_run = l_run * alpha + (ps0 + ps1);
;                     if (__builtin_amdgcn_ballot_w64(alpha != 1.0f) != 0ull) {
; #pragma unroll
;                         for (int db = 0; db < 4; ++db)
; #pragma unroll
;                             for (int r = 0; r < 16; ++r) O[db][r] *= alpha;
;                     }
;                 } else {
; #pragma unroll
;                     for (int r = 0; r < 16; ++r) { s0[r] *= sl2; s1[r] *= sl2; }
;                     if (need_bias || need_causal || need_win) {
; #pragma unroll
;                         for (int i = 0; i < 32; ++i) {
;                             const int s = kv0 + (i >> 3) * 16 + 8 * g + (i & 7);
;                             const int dist = t_lane - ((MODE == M_CMP) ? 16 * s + 31 : s);
;                             float v = (i < 16) ? s0[i & 15] : s1[i & 15];
;                             if (need_bias) { const int di = dist < 0 ? 0 : (dist > 128 ? 128 : dist); v += tb[di]; }
;                             bool msk = dist < 0;
;                             if (MODE == M_WIN) msk = msk || dist >= 512;
;                             if (msk) v = NEG;
;                             if (i < 16) s0[i & 15] = v; else s1[i & 15] = v;
;                             if ((i & 7) == 7) __builtin_amdgcn_sched_barrier(0);
;                         }
;                     }
;                     if (MODE == M_SLC) {
;                         if (!selbit) {
; #pragma unroll
;                             for (int r = 0; r < 16; ++r) { s0[r] = NEG; s1[r] = NEG; }
;                         }
;                     }
;                     if (!PASS2) {
;                         float mx = fmaxf(s0[0], s1[0]);
; #pragma unroll
;                         for (int r = 1; r < 16; ++r) mx = fmax3(mx, s0[r], s1[r]);
;                         mx = xhalf_max(mx);
;                         const float mn = (mx > m_run + 8.0f) ? mx : m_run;
;                         const float alpha = fexp2(m_run - mn);
;                         m_run = mn;
.Lfast_fox_norescale:
	v_fma_f32 v118, v98, s83, -v4
	v_fma_f32 v119, v99, s83, -v4
	v_exp_f32_e32 v6, v118
	v_exp_f32_e32 v7, v119
	v_fma_f32 v120, v100, s83, -v4
	v_fma_f32 v121, v101, s83, -v4
	v_exp_f32_e32 v8, v120
	v_exp_f32_e32 v9, v121
	v_add_f32_e32 v122, v6, v7
	v_fma_f32 v118, v102, s83, -v4
	v_fma_f32 v119, v103, s83, -v4
	v_exp_f32_e32 v114, v118
	v_exp_f32_e32 v115, v119
	v_cvt_pk_bf16_f32 v98, v6, v7
	v_add_f32_e32 v122, v122, v8
	v_fma_f32 v120, v104, s83, -v4
	v_add_f32_e32 v122, v122, v9
	v_fma_f32 v121, v105, s83, -v4
	v_exp_f32_e32 v116, v120
	v_exp_f32_e32 v117, v121
	v_cvt_pk_bf16_f32 v99, v8, v9
	v_add_f32_e32 v122, v122, v114
	v_add_f32_e32 v122, v122, v115
	v_cvt_pk_bf16_f32 v100, v114, v115
	v_add_f32_e32 v122, v122, v116
	v_add_f32_e32 v122, v122, v117
	v_cvt_pk_bf16_f32 v101, v116, v117
	v_fma_f32 v118, v106, s83, -v4
	v_fma_f32 v119, v107, s83, -v4
	s_waitcnt lgkmcnt(2)
	v_mfma_f32_32x32x16_bf16 v[66:81], v[240:243], v[98:101], v[66:81]
	v_exp_f32_e32 v6, v118
	v_exp_f32_e32 v7, v119
	v_fma_f32 v120, v108, s83, -v4
	v_fma_f32 v121, v109, s83, -v4
	v_exp_f32_e32 v8, v120
	v_exp_f32_e32 v9, v121
	s_waitcnt lgkmcnt(1)
	v_mfma_f32_32x32x16_bf16 v[50:65], v[244:247], v[98:101], v[50:65]
	ds_read_b128 v[240:243], v252 offset:48640
	v_add_f32_e32 v122, v122, v6
	v_fma_f32 v118, v110, s83, -v4
	v_add_f32_e32 v122, v122, v7
	v_fma_f32 v119, v111, s83, -v4
	v_exp_f32_e32 v114, v118
	v_exp_f32_e32 v115, v119
	s_waitcnt lgkmcnt(1)
	v_mfma_f32_32x32x16_bf16 v[34:49], v[248:251], v[98:101], v[34:49]
	ds_read_b128 v[244:247], v252 offset:34848
	v_cvt_pk_bf16_f32 v106, v6, v7
	v_add_f32_e32 v122, v122, v8
	v_fma_f32 v120, v112, s83, -v4
	v_add_f32_e32 v122, v122, v9
	v_fma_f32 v121, v113, s83, -v4
	v_exp_f32_e32 v116, v120
	s_waitcnt lgkmcnt(1)
	v_mfma_f32_32x32x16_bf16 v[18:33], v[240:243], v[98:101], v[18:33]
	ds_read_b128 v[248:251], v252 offset:39456
	v_exp_f32_e32 v117, v121
	v_cvt_pk_bf16_f32 v107, v8, v9
	v_add_f32_e32 v122, v122, v114
	v_add_f32_e32 v122, v122, v115
	v_cvt_pk_bf16_f32 v108, v114, v115
	v_add_f32_e32 v122, v122, v116
	v_add_f32_e32 v122, v122, v117
	v_cvt_pk_bf16_f32 v109, v116, v117
	v_fma_f32 v118, v82, s83, -v4
	v_fma_f32 v119, v83, s83, -v4
	s_waitcnt lgkmcnt(1)
	v_mfma_f32_32x32x16_bf16 v[66:81], v[244:247], v[106:109], v[66:81]
	ds_read_b128 v[240:243], v252 offset:44064
	v_exp_f32_e32 v6, v118
	v_exp_f32_e32 v7, v119
	v_fma_f32 v120, v84, s83, -v4
	v_fma_f32 v121, v85, s83, -v4
	v_exp_f32_e32 v8, v120
	v_exp_f32_e32 v9, v121
	s_waitcnt lgkmcnt(1)
	v_mfma_f32_32x32x16_bf16 v[50:65], v[248:251], v[106:109], v[50:65]
	ds_read_b128 v[244:247], v252 offset:48672
	v_add_f32_e32 v123, v6, v7
	v_fma_f32 v118, v86, s83, -v4
	v_fma_f32 v119, v87, s83, -v4
	v_exp_f32_e32 v114, v118
	v_exp_f32_e32 v115, v119
	v_cvt_pk_bf16_f32 v82, v6, v7
	s_waitcnt lgkmcnt(1)
	v_mfma_f32_32x32x16_bf16 v[34:49], v[240:243], v[106:109], v[34:49]
	ds_read_b128 v[248:251], v252 offset:34880
	v_add_f32_e32 v123, v123, v8
	v_fma_f32 v120, v88, s83, -v4
	v_add_f32_e32 v123, v123, v9
	v_fma_f32 v121, v89, s83, -v4
	v_exp_f32_e32 v116, v120
	v_exp_f32_e32 v117, v121
	s_waitcnt lgkmcnt(1)
	v_mfma_f32_32x32x16_bf16 v[18:33], v[244:247], v[106:109], v[18:33]
	ds_read_b128 v[240:243], v252 offset:39488
	v_cvt_pk_bf16_f32 v83, v8, v9
	v_add_f32_e32 v123, v123, v114
	v_add_f32_e32 v123, v123, v115
	v_cvt_pk_bf16_f32 v84, v114, v115
	v_add_f32_e32 v123, v123, v116
	v_add_f32_e32 v123, v123, v117
	v_cvt_pk_bf16_f32 v85, v116, v117
	v_fma_f32 v118, v90, s83, -v4
	v_fma_f32 v119, v91, s83, -v4
	s_waitcnt lgkmcnt(1)
	v_mfma_f32_32x32x16_bf16 v[66:81], v[248:251], v[82:85], v[66:81]
	ds_read_b128 v[244:247], v252 offset:44096
	v_exp_f32_e32 v6, v118
	v_exp_f32_e32 v7, v119
	v_fma_f32 v120, v92, s83, -v4
	v_fma_f32 v121, v93, s83, -v4
	v_exp_f32_e32 v8, v120
	v_exp_f32_e32 v9, v121
	s_waitcnt lgkmcnt(1)
	v_mfma_f32_32x32x16_bf16 v[50:65], v[240:243], v[82:85], v[50:65]
	ds_read_b128 v[248:251], v252 offset:48704
	v_add_f32_e32 v123, v123, v6
	v_fma_f32 v118, v94, s83, -v4
	v_add_f32_e32 v123, v123, v7
	v_fma_f32 v119, v95, s83, -v4
	v_exp_f32_e32 v114, v118
	v_exp_f32_e32 v115, v119
	s_waitcnt lgkmcnt(1)
	v_mfma_f32_32x32x16_bf16 v[34:49], v[244:247], v[82:85], v[34:49]
	ds_read_b128 v[240:243], v252 offset:34912
	v_cvt_pk_bf16_f32 v90, v6, v7
	v_add_f32_e32 v123, v123, v8
	v_fma_f32 v120, v96, s83, -v4
	v_add_f32_e32 v123, v123, v9
	v_fma_f32 v121, v97, s83, -v4
	v_exp_f32_e32 v116, v120
	s_waitcnt lgkmcnt(1)
	v_mfma_f32_32x32x16_bf16 v[18:33], v[248:251], v[82:85], v[18:33]
	ds_read_b128 v[244:247], v252 offset:39520
	v_exp_f32_e32 v117, v121
	v_cvt_pk_bf16_f32 v91, v8, v9
	v_add_f32_e32 v123, v123, v114
	v_add_f32_e32 v123, v123, v115
	v_cvt_pk_bf16_f32 v92, v114, v115
	v_add_f32_e32 v123, v123, v116
	v_add_f32_e32 v123, v123, v117
	v_cvt_pk_bf16_f32 v93, v116, v117
	v_add_f32_e32 v5, v122, v123
	s_waitcnt lgkmcnt(1)
	v_mfma_f32_32x32x16_bf16 v[66:81], v[240:243], v[90:93], v[66:81]
	ds_read_b128 v[248:251], v252 offset:44128
	v_fmac_f32_e32 v5, v238, v2
	s_waitcnt lgkmcnt(1)
	v_mfma_f32_32x32x16_bf16 v[50:65], v[244:247], v[90:93], v[50:65]
	ds_read_b128 v[240:243], v252 offset:48736
	s_waitcnt lgkmcnt(1)
	v_mfma_f32_32x32x16_bf16 v[34:49], v[248:251], v[90:93], v[34:49]
	s_waitcnt lgkmcnt(0)
	v_mfma_f32_32x32x16_bf16 v[18:33], v[240:243], v[90:93], v[18:33]
	s_nop 0
	s_and_b64 vcc, exec, s[10:11]
	s_cbranch_vccnz .Lpostpv_fox
	s_waitcnt vmcnt(0)
	v_mov_b32_e32 v2, v145
	s_branch .Lfox_cn_ready
	s_branch .Lpostpv_fox

; #define LAS __attribute__((address_space(3)))
; __device__ __forceinline__ float fexp2(float x) { return __builtin_amdgcn_exp2f(x); }
; __device__ __forceinline__ float fmax3(float a, float b, float c) { float d; asm("v_max3_f32 %0, %1, %2, %3" : "=v"(d) : "v"(a), "v"(b), "v"(c)); return d; }
; __device__ __forceinline__ f32x16 mfma32(bf16x8 a, bf16x8 b, f32x16 c) { return __builtin_amdgcn_mfma_f32_32x32x16_bf16(a, b, c, 0, 0, 0); }
; template <int MODE, int DK, bool PASS2> ...
;     ...
;                 const LAS unsigned char* kb = lds + F_KB0 + buf * F_KBS + g * 16 + prow * KSTR;
;                 __builtin_amdgcn_s_setprio(1);
; #pragma unroll
;                 for (int kk = 0; kk < DK / 16; ++kk) {
;                     const bf16x8 a0 = *(const LAS bf16x8*)(kb + kk * 32);
;                     const bf16x8 a1 = *(const LAS bf16x8*)(kb + 32 * KSTR + kk * 32);
;                     s0 = mfma32(a0, qf[kk], s0); s1 = mfma32(a1, qf[kk], s1);
;                 }
;                 __builtin_amdgcn_s_setprio(0);
;                 const bool need_causal = pos_max > t_wmin;
;                 const bool need_bias = (MODE != M_FOX) && ((t_wmin - pos_max) < 128);
;                 const bool need_win = (MODE == M_WIN) && (t_wmax - pos_min >= 512);
;                 if (!PASS2 && !(need_causal || need_bias || need_win)) {
;                     float mx = fmaxf(s0[0], s1[0]);
; #pragma unroll
;                     for (int r = 1; r < 16; ++r) mx = fmax3(mx, s0[r], s1[r]);
;                     if (MODE == M_SLC) mx = selbit ? mx : NEG;
;                     mx = xhalf_max(mx);
;                     const float mxs = mx * sl2;
;                     const float mn = (mxs > m_run + 8.0f) ? mxs : m_run;
;                     const float alpha = fexp2(m_run - mn);
;                     m_run = mn;
;                     float nm = -mn;
;                     if (MODE == M_SLC) nm = selbit ? nm : -__builtin_inff();
;                     float ps0 = 0.f, ps1 = 0.f;
; #pragma unroll
;                     for (int r = 0; r < 16; ++r) {
;                         s0[r] = fexp2(__builtin_fmaf(s0[r], sl2, nm)); s1[r] = fexp2(__builtin_fmaf(s1[r], sl2, nm));
;                         ps0 += s0[r]; ps1 += s1[r];
;                     }
;                     l_run = l_run * alpha + (ps0 + ps1);
;                     if (__builtin_amdgcn_ballot_w64(alpha != 1.0f) != 0ull) {
.LBB0_2131:
	s_mul_i32 s4, s58, 0x4400
	v_add_u32_e32 v16, s4, v202
	s_setprio 1
	ds_read_b128 v[4:7], v16
	ds_read_b128 v[8:11], v16 offset:32
	s_waitcnt lgkmcnt(1)
	v_mfma_f32_32x32x16_bf16 v[82:97], v[4:7], v[114:117], 0
	ds_read_b128 v[4:7], v16 offset:4608
	ds_read_b128 v[12:15], v16 offset:4640
	s_waitcnt lgkmcnt(1)
	v_mfma_f32_32x32x16_bf16 v[98:113], v[4:7], v[114:117], 0
	v_mfma_f32_32x32x16_bf16 v[82:97], v[8:11], v[118:121], v[82:97]
	ds_read_b128 v[4:7], v16 offset:64
	ds_read_b128 v[8:11], v16 offset:96
	s_waitcnt lgkmcnt(2)
	v_mfma_f32_32x32x16_bf16 v[98:113], v[12:15], v[118:121], v[98:113]
	s_waitcnt lgkmcnt(1)
	v_mfma_f32_32x32x16_bf16 v[82:97], v[4:7], v[122:125], v[82:97]
	ds_read_b128 v[4:7], v16 offset:4672
	ds_read_b128 v[12:15], v16 offset:4704
	s_waitcnt lgkmcnt(1)
	v_mfma_f32_32x32x16_bf16 v[98:113], v[4:7], v[122:125], v[98:113]
	v_mfma_f32_32x32x16_bf16 v[82:97], v[8:11], v[126:129], v[82:97]
	s_waitcnt lgkmcnt(0)
	v_mfma_f32_32x32x16_bf16 v[98:113], v[12:15], v[126:129], v[98:113]
	s_nop 0
	v_add_u32_e32 v4, s8, v196
	v_cmp_le_i32_e32 vcc, s57, v193
	v_cmp_lt_i32_e64 s[6:7], s52, v4
	v_cmp_gt_i32_e64 s[4:5], s51, v4
	s_and_b64 s[6:7], vcc, s[6:7]
	v_add_f32_e32 v208, 0x41000000, v178
	s_and_saveexec_b64 s[28:29], s[6:7]
	s_xor_b64 s[6:7], exec, s[28:29]
	s_cbranch_execz .LBB0_2135
	s_cmp_eq_u64 s[6:7], 0
	s_cbranch_scc1 .Lfast_diff
	s_nop 1
	v_max_f32_e32 v4, v98, v98
	v_max_f32_e32 v5, v82, v82
	v_max_f32_e32 v4, v5, v4
	v_max3_f32 v4, v4, v83, v99
	s_nop 0
	v_max3_f32 v4, v4, v84, v100
	s_nop 0
	v_max3_f32 v4, v4, v85, v101
	s_nop 0
	v_max3_f32 v4, v4, v86, v102
	s_nop 0
	v_max3_f32 v4, v4, v87, v103
	s_nop 0
	v_max3_f32 v4, v4, v88, v104
	s_nop 0
	v_max3_f32 v4, v4, v89, v105
	s_nop 0
	v_max3_f32 v4, v4, v90, v106
	s_nop 0
	v_max3_f32 v4, v4, v91, v107
	s_nop 0
	v_max3_f32 v4, v4, v92, v108
	s_nop 0
	v_max3_f32 v4, v4, v93, v109
	s_nop 0
	v_max3_f32 v4, v4, v94, v110
	s_nop 0
	v_max3_f32 v4, v4, v95, v111
	s_nop 0
	v_max3_f32 v4, v4, v96, v112
	s_nop 0
	v_max3_f32 v4, v4, v97, v113
	s_nop 0
	v_mov_b32_e32 v5, v4
	s_nop 1
	v_permlane32_swap_b32_e32 v4, v5
	v_max_f32_e32 v5, v5, v5
	v_max_f32_e32 v4, v4, v4
	v_max_f32_e32 v4, v4, v5
	v_mul_f32_e32 v4, 0x3e38aa3b, v4
	v_cmp_gt_f32_e32 vcc, v4, v208
	s_nop 1
	v_cndmask_b32_e32 v207, v178, v4, vcc
	v_sub_f32_e32 v4, v178, v207
	v_exp_f32_e32 v178, v4
	s_nop 0
	v_cmp_neq_f32_e32 vcc, 1.0, v178
	s_cbranch_vccz .LBB0_2134
	v_pk_mul_f32 v[80:81], v[80:81], v[178:179] op_sel_hi:[1,0]
	v_pk_mul_f32 v[78:79], v[78:79], v[178:179] op_sel_hi:[1,0]
	v_pk_mul_f32 v[76:77], v[76:77], v[178:179] op_sel_hi:[1,0]
	v_pk_mul_f32 v[74:75], v[74:75], v[178:179] op_sel_hi:[1,0]
	v_pk_mul_f32 v[72:73], v[72:73], v[178:179] op_sel_hi:[1,0]
	v_pk_mul_f32 v[70:71], v[70:71], v[178:179] op_sel_hi:[1,0]
	v_pk_mul_f32 v[68:69], v[68:69], v[178:179] op_sel_hi:[1,0]
	v_pk_mul_f32 v[66:67], v[66:67], v[178:179] op_sel_hi:[1,0]
	v_pk_mul_f32 v[64:65], v[64:65], v[178:179] op_sel_hi:[1,0]
	v_pk_mul_f32 v[62:63], v[62:63], v[178:179] op_sel_hi:[1,0]
	v_pk_mul_f32 v[60:61], v[60:61], v[178:179] op_sel_hi:[1,0]
	v_pk_mul_f32 v[58:59], v[58:59], v[178:179] op_sel_hi:[1,0]
	v_pk_mul_f32 v[56:57], v[56:57], v[178:179] op_sel_hi:[1,0]
	v_pk_mul_f32 v[54:55], v[54:55], v[178:179] op_sel_hi:[1,0]
	v_pk_mul_f32 v[52:53], v[52:53], v[178:179] op_sel_hi:[1,0]
	v_pk_mul_f32 v[50:51], v[50:51], v[178:179] op_sel_hi:[1,0]
	v_pk_mul_f32 v[48:49], v[48:49], v[178:179] op_sel_hi:[1,0]
	v_pk_mul_f32 v[46:47], v[46:47], v[178:179] op_sel_hi:[1,0]
	v_pk_mul_f32 v[44:45], v[44:45], v[178:179] op_sel_hi:[1,0]
	v_pk_mul_f32 v[42:43], v[42:43], v[178:179] op_sel_hi:[1,0]
	v_pk_mul_f32 v[40:41], v[40:41], v[178:179] op_sel_hi:[1,0]
	v_pk_mul_f32 v[38:39], v[38:39], v[178:179] op_sel_hi:[1,0]
	v_pk_mul_f32 v[36:37], v[36:37], v[178:179] op_sel_hi:[1,0]
	v_pk_mul_f32 v[34:35], v[34:35], v[178:179] op_sel_hi:[1,0]
	v_pk_mul_f32 v[32:33], v[32:33], v[178:179] op_sel_hi:[1,0]
	v_pk_mul_f32 v[30:31], v[30:31], v[178:179] op_sel_hi:[1,0]
	v_pk_mul_f32 v[28:29], v[28:29], v[178:179] op_sel_hi:[1,0]
	v_pk_mul_f32 v[26:27], v[26:27], v[178:179] op_sel_hi:[1,0]
	v_pk_mul_f32 v[24:25], v[24:25], v[178:179] op_sel_hi:[1,0]
	v_pk_mul_f32 v[22:23], v[22:23], v[178:179] op_sel_hi:[1,0]
	v_pk_mul_f32 v[20:21], v[20:21], v[178:179] op_sel_hi:[1,0]
	v_pk_mul_f32 v[18:19], v[18:19], v[178:179] op_sel_hi:[1,0]

; template <int MODE, int DK, bool PASS2> ...
;     ...
;                     float ps0 = 0.f, ps1 = 0.f;
; #pragma unroll
;                     for (int r = 0; r < 16; ++r) {
;                         s0[r] = fexp2(__builtin_fmaf(s0[r], sl2, nm)); s1[r] = fexp2(__builtin_fmaf(s1[r], sl2, nm));
;                         ps0 += s0[r]; ps1 += s1[r];
;                     }
;                     l_run = l_run * alpha + (ps0 + ps1);
;                     if (__builtin_amdgcn_ballot_w64(alpha != 1.0f) != 0ull) {
; #pragma unroll
;                         for (int db = 0; db < 4; ++db)
; #pragma unroll
;                             for (int r = 0; r < 16; ++r) O[db][r] *= alpha;
;                     }
;                 } else {
; #pragma unroll
;                     for (int r = 0; r < 16; ++r) { s0[r] *= sl2; s1[r] *= sl2; }
;                     if (need_bias || need_causal || need_win) {
; #pragma unroll
;                         for (int i = 0; i < 32; ++i) {
;                             const int s = kv0 + (i >> 3) * 16 + 8 * g + (i & 7);
;                             const int dist = t_lane - ((MODE == M_CMP) ? 16 * s + 31 : s);
;                             float v = (i < 16) ? s0[i & 15] : s1[i & 15];
;                             if (need_bias) { const int di = dist < 0 ? 0 : (dist > 128 ? 128 : dist); v += tb[di]; }
;                             bool msk = dist < 0;
;                             if (MODE == M_WIN) msk = msk || dist >= 512;
;                             if (msk) v = NEG;
;                             if (i < 16) s0[i & 15] = v; else s1[i & 15] = v;
;                             if ((i & 7) == 7) __builtin_amdgcn_sched_barrier(0);
;                         }
;                     }
;                     if (MODE == M_SLC) {
;                         if (!selbit) {
; #pragma unroll
;                             for (int r = 0; r < 16; ++r) { s0[r] = NEG; s1[r] = NEG; }
;                         }
;                     }
;                     if (!PASS2) {
;                         float mx = fmaxf(s0[0], s1[0]);
; #pragma unroll
;                         for (int r = 1; r < 16; ++r) mx = fmax3(mx, s0[r], s1[r]);
;                         mx = xhalf_max(mx);
;                         const float mn = (mx > m_run + 8.0f) ? mx : m_run;
;                         const float alpha = fexp2(m_run - mn);
;                         m_run = mn;
.Lfast_diff_norescale:
	v_fma_f32 v12, v82, s12, -v207
	v_fma_f32 v13, v83, s12, -v207
	v_exp_f32_e32 v4, v12
	v_exp_f32_e32 v5, v13
	v_fma_f32 v14, v84, s12, -v207
	v_fma_f32 v15, v85, s12, -v207
	v_exp_f32_e32 v6, v14
	v_exp_f32_e32 v7, v15
	v_add_f32_e32 v16, v4, v5
	v_fma_f32 v12, v86, s12, -v207
	v_fma_f32 v13, v87, s12, -v207
	v_exp_f32_e32 v8, v12
	v_exp_f32_e32 v9, v13
	v_cvt_pk_bf16_f32 v236, v4, v5
	v_add_f32_e32 v16, v16, v6
	v_fma_f32 v14, v88, s12, -v207
	v_add_f32_e32 v16, v16, v7
	v_fma_f32 v15, v89, s12, -v207
	v_exp_f32_e32 v10, v14
	v_exp_f32_e32 v11, v15
	v_cvt_pk_bf16_f32 v237, v6, v7
	v_add_f32_e32 v16, v16, v8
	v_add_f32_e32 v16, v16, v9
	v_cvt_pk_bf16_f32 v238, v8, v9
	v_add_f32_e32 v16, v16, v10
	v_add_f32_e32 v16, v16, v11
	v_cvt_pk_bf16_f32 v239, v10, v11
	v_fma_f32 v12, v90, s12, -v207
	v_fma_f32 v13, v91, s12, -v207
	s_waitcnt lgkmcnt(5)
	v_mfma_f32_32x32x16_bf16 v[66:81], v[212:215], v[236:239], v[66:81]
	v_exp_f32_e32 v4, v12
	v_exp_f32_e32 v5, v13
	v_fma_f32 v14, v92, s12, -v207
	v_fma_f32 v15, v93, s12, -v207
	v_exp_f32_e32 v6, v14
	v_exp_f32_e32 v7, v15
	s_waitcnt lgkmcnt(4)
	v_mfma_f32_32x32x16_bf16 v[50:65], v[216:219], v[236:239], v[50:65]
	ds_read_b128 v[212:215], v210 offset:44064
	v_add_f32_e32 v16, v16, v4
	v_fma_f32 v12, v94, s12, -v207
	v_add_f32_e32 v16, v16, v5
	v_fma_f32 v13, v95, s12, -v207
	v_exp_f32_e32 v8, v12
	v_exp_f32_e32 v9, v13
	s_waitcnt lgkmcnt(4)
	v_mfma_f32_32x32x16_bf16 v[34:49], v[220:223], v[236:239], v[34:49]
	ds_read_b128 v[216:219], v210 offset:48672
	v_cvt_pk_bf16_f32 v240, v4, v5
	v_add_f32_e32 v16, v16, v6
	v_fma_f32 v14, v96, s12, -v207
	v_add_f32_e32 v16, v16, v7
	v_fma_f32 v15, v97, s12, -v207
	v_exp_f32_e32 v10, v14
	s_waitcnt lgkmcnt(4)
	v_mfma_f32_32x32x16_bf16 v[18:33], v[224:227], v[236:239], v[18:33]
	ds_read_b128 v[220:223], v210 offset:34880
	v_exp_f32_e32 v11, v15
	v_cvt_pk_bf16_f32 v241, v6, v7
	v_add_f32_e32 v16, v16, v8
	v_add_f32_e32 v16, v16, v9
	v_cvt_pk_bf16_f32 v242, v8, v9
	v_add_f32_e32 v16, v16, v10
	v_add_f32_e32 v16, v16, v11
	v_cvt_pk_bf16_f32 v243, v10, v11
	v_fma_f32 v12, v98, s12, -v207
	v_fma_f32 v13, v99, s12, -v207
	s_waitcnt lgkmcnt(4)
	v_mfma_f32_32x32x16_bf16 v[66:81], v[228:231], v[240:243], v[66:81]
	ds_read_b128 v[224:227], v210 offset:39488
	v_exp_f32_e32 v4, v12
	v_exp_f32_e32 v5, v13
	v_fma_f32 v14, v100, s12, -v207
	v_fma_f32 v15, v101, s12, -v207
	v_exp_f32_e32 v6, v14
	v_exp_f32_e32 v7, v15
	s_waitcnt lgkmcnt(4)
	v_mfma_f32_32x32x16_bf16 v[50:65], v[232:235], v[240:243], v[50:65]
	ds_read_b128 v[228:231], v210 offset:44096
	v_add_f32_e32 v17, v4, v5
	v_fma_f32 v12, v102, s12, -v207
	v_fma_f32 v13, v103, s12, -v207
	v_exp_f32_e32 v8, v12
	v_exp_f32_e32 v9, v13
	v_cvt_pk_bf16_f32 v244, v4, v5
	s_waitcnt lgkmcnt(4)
	v_mfma_f32_32x32x16_bf16 v[34:49], v[212:215], v[240:243], v[34:49]
	ds_read_b128 v[232:235], v210 offset:48704
	v_add_f32_e32 v17, v17, v6
	v_fma_f32 v14, v104, s12, -v207
	v_add_f32_e32 v17, v17, v7
	v_fma_f32 v15, v105, s12, -v207
	v_exp_f32_e32 v10, v14
	v_exp_f32_e32 v11, v15
	s_waitcnt lgkmcnt(4)
	v_mfma_f32_32x32x16_bf16 v[18:33], v[216:219], v[240:243], v[18:33]
	ds_read_b128 v[212:215], v210 offset:34912
	v_cvt_pk_bf16_f32 v245, v6, v7
	v_add_f32_e32 v17, v17, v8
	v_add_f32_e32 v17, v17, v9
	v_cvt_pk_bf16_f32 v246, v8, v9
	v_add_f32_e32 v17, v17, v10
	v_add_f32_e32 v17, v17, v11
	v_cvt_pk_bf16_f32 v247, v10, v11
	v_fma_f32 v12, v106, s12, -v207
	v_fma_f32 v13, v107, s12, -v207
	s_waitcnt lgkmcnt(4)
	v_mfma_f32_32x32x16_bf16 v[66:81], v[220:223], v[244:247], v[66:81]
	ds_read_b128 v[216:219], v210 offset:39520
	v_exp_f32_e32 v4, v12
	v_exp_f32_e32 v5, v13
	v_fma_f32 v14, v108, s12, -v207
	v_fma_f32 v15, v109, s12, -v207
	v_exp_f32_e32 v6, v14
	v_exp_f32_e32 v7, v15
	s_waitcnt lgkmcnt(4)
	v_mfma_f32_32x32x16_bf16 v[50:65], v[224:227], v[244:247], v[50:65]
	ds_read_b128 v[220:223], v210 offset:44128
	v_add_f32_e32 v17, v17, v4
	v_fma_f32 v12, v110, s12, -v207
	v_add_f32_e32 v17, v17, v5
	v_fma_f32 v13, v111, s12, -v207
	v_exp_f32_e32 v8, v12
	v_exp_f32_e32 v9, v13
	s_waitcnt lgkmcnt(4)
	v_mfma_f32_32x32x16_bf16 v[34:49], v[228:231], v[244:247], v[34:49]
	ds_read_b128 v[224:227], v210 offset:48736
	v_cvt_pk_bf16_f32 v248, v4, v5
	v_add_f32_e32 v17, v17, v6
	v_fma_f32 v14, v112, s12, -v207
	v_add_f32_e32 v17, v17, v7
	v_fma_f32 v15, v113, s12, -v207
	v_exp_f32_e32 v10, v14
	s_waitcnt lgkmcnt(4)
	v_mfma_f32_32x32x16_bf16 v[18:33], v[232:235], v[244:247], v[18:33]
	v_exp_f32_e32 v11, v15
	v_cvt_pk_bf16_f32 v249, v6, v7
	v_add_f32_e32 v17, v17, v8
	v_add_f32_e32 v17, v17, v9
	v_cvt_pk_bf16_f32 v250, v8, v9
	v_add_f32_e32 v17, v17, v10
	v_add_f32_e32 v17, v17, v11
	v_cvt_pk_bf16_f32 v251, v10, v11
	v_add_f32_e32 v209, v16, v17
	s_waitcnt lgkmcnt(3)
	v_mfma_f32_32x32x16_bf16 v[66:81], v[212:215], v[248:251], v[66:81]
	v_fmac_f32_e32 v209, v206, v178
	s_waitcnt lgkmcnt(2)
	v_mfma_f32_32x32x16_bf16 v[50:65], v[216:219], v[248:251], v[50:65]
	s_waitcnt lgkmcnt(1)
	v_mfma_f32_32x32x16_bf16 v[34:49], v[220:223], v[248:251], v[34:49]
	s_waitcnt lgkmcnt(0)
	v_mfma_f32_32x32x16_bf16 v[18:33], v[224:227], v[248:251], v[18:33]
	s_nop 0
	s_branch .Lpostpv_diff

; template <int MODE, int DK, bool PASS2> ...
;     ...
;             bool active = pos_min <= t_wmax;
;             if (MODE == M_WIN) active = active && (t_wmin - pos_max < 512);
;             bool selbit = true;
;             if (MODE == M_SLC) {
;                 selbit = ((((const LAS unsigned*)impw)[j >> 5] >> (j & 31)) & 1u) != 0u;
;                 active = active && (__builtin_amdgcn_ballot_w64(selbit) != 0ull);
;             }
;             if (active) {
;                 f32x16 s0, s1;
;                 if (MODE == M_FOX) {
;                     const LAS float* ct = (const LAS float*)(lds + F_CT + buf * 256) + 8 * g;
; #pragma unroll
;                     for (int q4 = 0; q4 < 4; ++q4) {
;                         const f32x4 a = *(const LAS f32x4*)(ct + (q4 >> 1) * 16 + (q4 & 1) * 4), b = *(const LAS f32x4*)(ct + 32 + (q4 >> 1) * 16 + (q4 & 1) * 4);
; #pragma unroll
;                         for (int e = 0; e < 4; ++e) { s0[q4 * 4 + e] = a[e]; s1[q4 * 4 + e] = b[e]; }
;                     }
;                 } else { s0 = (f32x16)(0.f); s1 = (f32x16)(0.f); }
;                 const LAS unsigned char* kb = lds + F_KB0 + buf * F_KBS + g * 16 + prow * KSTR;
;                 __builtin_amdgcn_s_setprio(1);
; #pragma unroll
;                 for (int kk = 0; kk < DK / 16; ++kk) {
;                     const bf16x8 a0 = *(const LAS bf16x8*)(kb + kk * 32);
;                     const bf16x8 a1 = *(const LAS bf16x8*)(kb + 32 * KSTR + kk * 32);
;                     s0 = mfma32(a0, qf[kk], s0); s1 = mfma32(a1, qf[kk], s1);
;                 }
;                 __builtin_amdgcn_s_setprio(0);
;                 const bool need_causal = pos_max > t_wmin;
;                 const bool need_bias = (MODE != M_FOX) && ((t_wmin - pos_max) < 128);
;                 const bool need_win = (MODE == M_WIN) && (t_wmax - pos_min >= 512);
;                 if (!PASS2 && !(need_causal || need_bias || need_win)) {
;                     float mx = fmaxf(s0[0], s1[0]);
; #pragma unroll
;                     for (int r = 1; r < 16; ++r) mx = fmax3(mx, s0[r], s1[r]);
;                     if (MODE == M_SLC) mx = selbit ? mx : NEG;
;                     mx = xhalf_max(mx);
;                     const float mxs = mx * sl2;
;                     const float mn = (mxs > m_run + 8.0f) ? mxs : m_run;
;                     const float alpha = fexp2(m_run - mn);
.LBB0_2164:
	v_add_u32_e32 v2, 0xffffffa2, v201
	v_cmp_le_i32_e32 vcc, s88, v192
	v_cmp_gt_i32_e64 s[4:5], s82, v2
	s_and_b64 s[4:5], vcc, s[4:5]
	s_and_saveexec_b64 s[68:69], s[4:5]
	s_cbranch_execz .LBB0_2240
	s_mul_i32 s5, s89, 0x4400
	s_add_i32 s4, s88, 63
	v_add_u32_e32 v16, s5, v200
	s_setprio 1
	ds_read_b128 v[4:7], v16
	ds_read_b128 v[8:11], v16 offset:32
	s_waitcnt lgkmcnt(1)
	v_mfma_f32_32x32x16_bf16 v[98:113], v[4:7], v[114:117], 0
	ds_read_b128 v[4:7], v16 offset:8704
	ds_read_b128 v[12:15], v16 offset:8736
	s_waitcnt lgkmcnt(1)
	v_mfma_f32_32x32x16_bf16 v[82:97], v[4:7], v[114:117], 0
	v_mfma_f32_32x32x16_bf16 v[98:113], v[8:11], v[118:121], v[98:113]
	ds_read_b128 v[4:7], v16 offset:64
	ds_read_b128 v[8:11], v16 offset:96
	s_waitcnt lgkmcnt(2)
	v_mfma_f32_32x32x16_bf16 v[82:97], v[12:15], v[118:121], v[82:97]
	s_waitcnt lgkmcnt(1)
	v_mfma_f32_32x32x16_bf16 v[98:113], v[4:7], v[122:125], v[98:113]
	ds_read_b128 v[4:7], v16 offset:8768
	ds_read_b128 v[12:15], v16 offset:8800
	s_waitcnt lgkmcnt(1)
	v_mfma_f32_32x32x16_bf16 v[82:97], v[4:7], v[122:125], v[82:97]
	v_mfma_f32_32x32x16_bf16 v[98:113], v[8:11], v[126:129], v[98:113]
	ds_read_b128 v[4:7], v16 offset:128
	ds_read_b128 v[8:11], v16 offset:160
	s_waitcnt lgkmcnt(2)
	v_mfma_f32_32x32x16_bf16 v[82:97], v[12:15], v[126:129], v[82:97]
	s_waitcnt lgkmcnt(1)
	v_mfma_f32_32x32x16_bf16 v[98:113], v[4:7], v[130:133], v[98:113]
	ds_read_b128 v[4:7], v16 offset:8832
	ds_read_b128 v[12:15], v16 offset:8864
	s_waitcnt lgkmcnt(1)
	v_mfma_f32_32x32x16_bf16 v[82:97], v[4:7], v[130:133], v[82:97]
	v_mfma_f32_32x32x16_bf16 v[98:113], v[8:11], v[134:137], v[98:113]
	ds_read_b128 v[4:7], v16 offset:192
	ds_read_b128 v[8:11], v16 offset:224
	s_waitcnt lgkmcnt(2)
	v_mfma_f32_32x32x16_bf16 v[82:97], v[12:15], v[134:137], v[82:97]
	s_waitcnt lgkmcnt(1)
	v_mfma_f32_32x32x16_bf16 v[98:113], v[4:7], v[138:141], v[98:113]
	ds_read_b128 v[4:7], v16 offset:8896
	ds_read_b128 v[12:15], v16 offset:8928
	s_waitcnt lgkmcnt(1)
	v_mfma_f32_32x32x16_bf16 v[82:97], v[4:7], v[138:141], v[82:97]
	v_mfma_f32_32x32x16_bf16 v[98:113], v[8:11], v[142:145], v[98:113]
	s_waitcnt lgkmcnt(0)
	v_mfma_f32_32x32x16_bf16 v[82:97], v[12:15], v[142:145], v[82:97]
	s_nop 0
	v_cmp_gt_i32_e32 vcc, s4, v190
	v_cmp_lt_i32_e64 s[6:7], s45, v201
	v_cmp_gt_i32_e64 s[4:5], s76, v2
	s_or_b64 s[8:9], vcc, s[6:7]
	s_nor_b64 s[8:9], s[8:9], s[4:5]
	v_add_f32_e32 v2, 0x41000000, v207
	s_and_saveexec_b64 s[10:11], s[8:9]
	s_xor_b64 s[8:9], exec, s[10:11]
	s_cbranch_execz .LBB0_2169
	s_cmp_eq_u64 s[8:9], 0
	s_cbranch_scc1 .Lfast_win
	s_nop 1
	v_max_f32_e32 v4, v82, v82
	v_max_f32_e32 v5, v98, v98
	v_max_f32_e32 v4, v5, v4
	v_max3_f32 v4, v4, v99, v83
	s_nop 0
	v_max3_f32 v4, v4, v100, v84
	s_nop 0
	v_max3_f32 v4, v4, v101, v85
	s_nop 0
	v_max3_f32 v4, v4, v102, v86
	s_nop 0
	v_max3_f32 v4, v4, v103, v87
	s_nop 0
	v_max3_f32 v4, v4, v104, v88
	s_nop 0
	v_max3_f32 v4, v4, v105, v89
	s_nop 0
	v_max3_f32 v4, v4, v106, v90
	s_nop 0
	v_max3_f32 v4, v4, v107, v91
	s_nop 0
	v_max3_f32 v4, v4, v108, v92
	s_nop 0
	v_max3_f32 v4, v4, v109, v93
	s_nop 0
	v_max3_f32 v4, v4, v110, v94
	s_nop 0
	v_max3_f32 v4, v4, v111, v95
	s_nop 0
	v_max3_f32 v4, v4, v112, v96
	s_nop 0
	v_max3_f32 v4, v4, v113, v97
	s_nop 0
	v_mov_b32_e32 v5, v4
	s_nop 1
	v_permlane32_swap_b32_e32 v4, v5
	v_max_f32_e32 v5, v5, v5
	v_max_f32_e32 v4, v4, v4
	v_max_f32_e32 v4, v4, v5
	v_mul_f32_e32 v4, 0x3e0293ee, v4
	v_cmp_gt_f32_e32 vcc, v4, v2
	s_nop 1
	v_cndmask_b32_e32 v208, v207, v4, vcc
	v_sub_f32_e32 v2, v207, v208
	v_exp_f32_e32 v2, v2
	s_nop 0
	v_cmp_neq_f32_e32 vcc, 1.0, v2
	s_cbranch_vccz .LBB0_2168
	v_pk_mul_f32 v[80:81], v[80:81], v[2:3] op_sel_hi:[1,0]
	v_pk_mul_f32 v[78:79], v[78:79], v[2:3] op_sel_hi:[1,0]
	v_pk_mul_f32 v[76:77], v[76:77], v[2:3] op_sel_hi:[1,0]
	v_pk_mul_f32 v[74:75], v[74:75], v[2:3] op_sel_hi:[1,0]
	v_pk_mul_f32 v[72:73], v[72:73], v[2:3] op_sel_hi:[1,0]
	v_pk_mul_f32 v[70:71], v[70:71], v[2:3] op_sel_hi:[1,0]
	v_pk_mul_f32 v[68:69], v[68:69], v[2:3] op_sel_hi:[1,0]
	v_pk_mul_f32 v[66:67], v[66:67], v[2:3] op_sel_hi:[1,0]
	v_pk_mul_f32 v[64:65], v[64:65], v[2:3] op_sel_hi:[1,0]
	v_pk_mul_f32 v[62:63], v[62:63], v[2:3] op_sel_hi:[1,0]
	v_pk_mul_f32 v[60:61], v[60:61], v[2:3] op_sel_hi:[1,0]
	v_pk_mul_f32 v[58:59], v[58:59], v[2:3] op_sel_hi:[1,0]
	v_pk_mul_f32 v[56:57], v[56:57], v[2:3] op_sel_hi:[1,0]
	v_pk_mul_f32 v[54:55], v[54:55], v[2:3] op_sel_hi:[1,0]
	v_pk_mul_f32 v[52:53], v[52:53], v[2:3] op_sel_hi:[1,0]
	v_pk_mul_f32 v[50:51], v[50:51], v[2:3] op_sel_hi:[1,0]
	v_pk_mul_f32 v[48:49], v[48:49], v[2:3] op_sel_hi:[1,0]
	v_pk_mul_f32 v[46:47], v[46:47], v[2:3] op_sel_hi:[1,0]
	v_pk_mul_f32 v[44:45], v[44:45], v[2:3] op_sel_hi:[1,0]
	v_pk_mul_f32 v[42:43], v[42:43], v[2:3] op_sel_hi:[1,0]
	v_pk_mul_f32 v[40:41], v[40:41], v[2:3] op_sel_hi:[1,0]
	v_pk_mul_f32 v[38:39], v[38:39], v[2:3] op_sel_hi:[1,0]
	v_pk_mul_f32 v[36:37], v[36:37], v[2:3] op_sel_hi:[1,0]
	v_pk_mul_f32 v[34:35], v[34:35], v[2:3] op_sel_hi:[1,0]
	v_pk_mul_f32 v[32:33], v[32:33], v[2:3] op_sel_hi:[1,0]
	v_pk_mul_f32 v[30:31], v[30:31], v[2:3] op_sel_hi:[1,0]
	v_pk_mul_f32 v[28:29], v[28:29], v[2:3] op_sel_hi:[1,0]
	v_pk_mul_f32 v[26:27], v[26:27], v[2:3] op_sel_hi:[1,0]
	v_pk_mul_f32 v[24:25], v[24:25], v[2:3] op_sel_hi:[1,0]
	v_pk_mul_f32 v[22:23], v[22:23], v[2:3] op_sel_hi:[1,0]
	v_pk_mul_f32 v[20:21], v[20:21], v[2:3] op_sel_hi:[1,0]
	v_pk_mul_f32 v[18:19], v[18:19], v[2:3] op_sel_hi:[1,0]

; template <int MODE, int DK, bool PASS2> ...
;     ...
;                     float ps0 = 0.f, ps1 = 0.f;
; #pragma unroll
;                     for (int r = 0; r < 16; ++r) {
;                         s0[r] = fexp2(__builtin_fmaf(s0[r], sl2, nm)); s1[r] = fexp2(__builtin_fmaf(s1[r], sl2, nm));
;                         ps0 += s0[r]; ps1 += s1[r];
;                     }
;                     l_run = l_run * alpha + (ps0 + ps1);
;                     if (__builtin_amdgcn_ballot_w64(alpha != 1.0f) != 0ull) {
; #pragma unroll
;                         for (int db = 0; db < 4; ++db)
; #pragma unroll
;                             for (int r = 0; r < 16; ++r) O[db][r] *= alpha;
;                     }
;                 } else {
; #pragma unroll
;                     for (int r = 0; r < 16; ++r) { s0[r] *= sl2; s1[r] *= sl2; }
;                     if (need_bias || need_causal || need_win) {
; #pragma unroll
;                         for (int i = 0; i < 32; ++i) {
;                             const int s = kv0 + (i >> 3) * 16 + 8 * g + (i & 7);
;                             const int dist = t_lane - ((MODE == M_CMP) ? 16 * s + 31 : s);
;                             float v = (i < 16) ? s0[i & 15] : s1[i & 15];
;                             if (need_bias) { const int di = dist < 0 ? 0 : (dist > 128 ? 128 : dist); v += tb[di]; }
;                             bool msk = dist < 0;
;                             if (MODE == M_WIN) msk = msk || dist >= 512;
;                             if (msk) v = NEG;
;                             if (i < 16) s0[i & 15] = v; else s1[i & 15] = v;
;                             if ((i & 7) == 7) __builtin_amdgcn_sched_barrier(0);
;                         }
;                     }
;                     if (MODE == M_SLC) {
;                         if (!selbit) {
; #pragma unroll
;                             for (int r = 0; r < 16; ++r) { s0[r] = NEG; s1[r] = NEG; }
;                         }
;                     }
;                     if (!PASS2) {
;                         float mx = fmaxf(s0[0], s1[0]);
; #pragma unroll
;                         for (int r = 1; r < 16; ++r) mx = fmax3(mx, s0[r], s1[r]);
;                         mx = xhalf_max(mx);
;                         const float mn = (mx > m_run + 8.0f) ? mx : m_run;
;                         const float alpha = fexp2(m_run - mn);
;                         m_run = mn;
.Lfast_win_norescale:
	v_fma_f32 v12, v98, s58, -v208
	v_fma_f32 v13, v99, s58, -v208
	v_exp_f32_e32 v4, v12
	v_exp_f32_e32 v5, v13
	v_fma_f32 v14, v100, s58, -v208
	v_fma_f32 v15, v101, s58, -v208
	v_exp_f32_e32 v6, v14
	v_exp_f32_e32 v7, v15
	v_add_f32_e32 v16, v4, v5
	v_fma_f32 v12, v102, s58, -v208
	v_fma_f32 v13, v103, s58, -v208
	v_exp_f32_e32 v8, v12
	v_exp_f32_e32 v9, v13
	v_cvt_pk_bf16_f32 v236, v4, v5
	v_add_f32_e32 v16, v16, v6
	v_fma_f32 v14, v104, s58, -v208
	v_add_f32_e32 v16, v16, v7
	v_fma_f32 v15, v105, s58, -v208
	v_exp_f32_e32 v10, v14
	v_exp_f32_e32 v11, v15
	v_cvt_pk_bf16_f32 v237, v6, v7
	v_add_f32_e32 v16, v16, v8
	v_add_f32_e32 v16, v16, v9
	v_cvt_pk_bf16_f32 v238, v8, v9
	v_add_f32_e32 v16, v16, v10
	v_add_f32_e32 v16, v16, v11
	v_cvt_pk_bf16_f32 v239, v10, v11
	v_fma_f32 v12, v106, s58, -v208
	v_fma_f32 v13, v107, s58, -v208
	s_waitcnt lgkmcnt(5)
	v_mfma_f32_32x32x16_bf16 v[66:81], v[212:215], v[236:239], v[66:81]
	v_exp_f32_e32 v4, v12
	v_exp_f32_e32 v5, v13
	v_fma_f32 v14, v108, s58, -v208
	v_fma_f32 v15, v109, s58, -v208
	v_exp_f32_e32 v6, v14
	v_exp_f32_e32 v7, v15
	s_waitcnt lgkmcnt(4)
	v_mfma_f32_32x32x16_bf16 v[50:65], v[216:219], v[236:239], v[50:65]
	ds_read_b128 v[212:215], v210 offset:44064
	v_add_f32_e32 v16, v16, v4
	v_fma_f32 v12, v110, s58, -v208
	v_add_f32_e32 v16, v16, v5
	v_fma_f32 v13, v111, s58, -v208
	v_exp_f32_e32 v8, v12
	v_exp_f32_e32 v9, v13
	s_waitcnt lgkmcnt(4)
	v_mfma_f32_32x32x16_bf16 v[34:49], v[220:223], v[236:239], v[34:49]
	ds_read_b128 v[216:219], v210 offset:48672
	v_cvt_pk_bf16_f32 v240, v4, v5
	v_add_f32_e32 v16, v16, v6
	v_fma_f32 v14, v112, s58, -v208
	v_add_f32_e32 v16, v16, v7
	v_fma_f32 v15, v113, s58, -v208
	v_exp_f32_e32 v10, v14
	s_waitcnt lgkmcnt(4)
	v_mfma_f32_32x32x16_bf16 v[18:33], v[224:227], v[236:239], v[18:33]
	ds_read_b128 v[220:223], v210 offset:34880
	v_exp_f32_e32 v11, v15
	v_cvt_pk_bf16_f32 v241, v6, v7
	v_add_f32_e32 v16, v16, v8
	v_add_f32_e32 v16, v16, v9
	v_cvt_pk_bf16_f32 v242, v8, v9
	v_add_f32_e32 v16, v16, v10
	v_add_f32_e32 v16, v16, v11
	v_cvt_pk_bf16_f32 v243, v10, v11
	v_fma_f32 v12, v82, s58, -v208
	v_fma_f32 v13, v83, s58, -v208
	s_waitcnt lgkmcnt(4)
	v_mfma_f32_32x32x16_bf16 v[66:81], v[228:231], v[240:243], v[66:81]
	ds_read_b128 v[224:227], v210 offset:39488
	v_exp_f32_e32 v4, v12
	v_exp_f32_e32 v5, v13
	v_fma_f32 v14, v84, s58, -v208
	v_fma_f32 v15, v85, s58, -v208
	v_exp_f32_e32 v6, v14
	v_exp_f32_e32 v7, v15
	s_waitcnt lgkmcnt(4)
	v_mfma_f32_32x32x16_bf16 v[50:65], v[232:235], v[240:243], v[50:65]
	ds_read_b128 v[228:231], v210 offset:44096
	v_add_f32_e32 v17, v4, v5
	v_fma_f32 v12, v86, s58, -v208
	v_fma_f32 v13, v87, s58, -v208
	v_exp_f32_e32 v8, v12
	v_exp_f32_e32 v9, v13
	v_cvt_pk_bf16_f32 v244, v4, v5
	s_waitcnt lgkmcnt(4)
	v_mfma_f32_32x32x16_bf16 v[34:49], v[212:215], v[240:243], v[34:49]
	ds_read_b128 v[232:235], v210 offset:48704
	v_add_f32_e32 v17, v17, v6
	v_fma_f32 v14, v88, s58, -v208
	v_add_f32_e32 v17, v17, v7
	v_fma_f32 v15, v89, s58, -v208
	v_exp_f32_e32 v10, v14
	v_exp_f32_e32 v11, v15
	s_waitcnt lgkmcnt(4)
	v_mfma_f32_32x32x16_bf16 v[18:33], v[216:219], v[240:243], v[18:33]
	ds_read_b128 v[212:215], v210 offset:34912
	v_cvt_pk_bf16_f32 v245, v6, v7
	v_add_f32_e32 v17, v17, v8
	v_add_f32_e32 v17, v17, v9
	v_cvt_pk_bf16_f32 v246, v8, v9
	v_add_f32_e32 v17, v17, v10
	v_add_f32_e32 v17, v17, v11
	v_cvt_pk_bf16_f32 v247, v10, v11
	v_fma_f32 v12, v90, s58, -v208
	v_fma_f32 v13, v91, s58, -v208
	s_waitcnt lgkmcnt(4)
	v_mfma_f32_32x32x16_bf16 v[66:81], v[220:223], v[244:247], v[66:81]
	ds_read_b128 v[216:219], v210 offset:39520
	v_exp_f32_e32 v4, v12
	v_exp_f32_e32 v5, v13
	v_fma_f32 v14, v92, s58, -v208
	v_fma_f32 v15, v93, s58, -v208
	v_exp_f32_e32 v6, v14
	v_exp_f32_e32 v7, v15
	s_waitcnt lgkmcnt(4)
	v_mfma_f32_32x32x16_bf16 v[50:65], v[224:227], v[244:247], v[50:65]
	ds_read_b128 v[220:223], v210 offset:44128
	v_add_f32_e32 v17, v17, v4
	v_fma_f32 v12, v94, s58, -v208
	v_add_f32_e32 v17, v17, v5
	v_fma_f32 v13, v95, s58, -v208
	v_exp_f32_e32 v8, v12
	v_exp_f32_e32 v9, v13
	s_waitcnt lgkmcnt(4)
	v_mfma_f32_32x32x16_bf16 v[34:49], v[228:231], v[244:247], v[34:49]
	ds_read_b128 v[224:227], v210 offset:48736
	v_cvt_pk_bf16_f32 v248, v4, v5
	v_add_f32_e32 v17, v17, v6
	v_fma_f32 v14, v96, s58, -v208
	v_add_f32_e32 v17, v17, v7
	v_fma_f32 v15, v97, s58, -v208
	v_exp_f32_e32 v10, v14
	s_waitcnt lgkmcnt(4)
	v_mfma_f32_32x32x16_bf16 v[18:33], v[232:235], v[244:247], v[18:33]
	v_exp_f32_e32 v11, v15
	v_cvt_pk_bf16_f32 v249, v6, v7
	v_add_f32_e32 v17, v17, v8
	v_add_f32_e32 v17, v17, v9
	v_cvt_pk_bf16_f32 v250, v8, v9
	v_add_f32_e32 v17, v17, v10
	v_add_f32_e32 v17, v17, v11
	v_cvt_pk_bf16_f32 v251, v10, v11
	v_add_f32_e32 v209, v16, v17
	s_waitcnt lgkmcnt(3)
	v_mfma_f32_32x32x16_bf16 v[66:81], v[212:215], v[248:251], v[66:81]
	v_fmac_f32_e32 v209, v206, v2
	s_waitcnt lgkmcnt(2)
	v_mfma_f32_32x32x16_bf16 v[50:65], v[216:219], v[248:251], v[50:65]
	s_waitcnt lgkmcnt(1)
	v_mfma_f32_32x32x16_bf16 v[34:49], v[220:223], v[248:251], v[34:49]
	s_waitcnt lgkmcnt(0)
	v_mfma_f32_32x32x16_bf16 v[18:33], v[224:227], v[248:251], v[18:33]
	s_nop 0
	s_branch .Lpostpv_win

; template <int MODE, int DK, bool PASS2> ...
;     ...
;             if (active) {
;                 f32x16 s0, s1;
;                 if (MODE == M_FOX) {
;                     const LAS float* ct = (const LAS float*)(lds + F_CT + buf * 256) + 8 * g;
; #pragma unroll
;                     for (int q4 = 0; q4 < 4; ++q4) {
;                         const f32x4 a = *(const LAS f32x4*)(ct + (q4 >> 1) * 16 + (q4 & 1) * 4), b = *(const LAS f32x4*)(ct + 32 + (q4 >> 1) * 16 + (q4 & 1) * 4);
; #pragma unroll
;                         for (int e = 0; e < 4; ++e) { s0[q4 * 4 + e] = a[e]; s1[q4 * 4 + e] = b[e]; }
;                     }
;                 } else { s0 = (f32x16)(0.f); s1 = (f32x16)(0.f); }
;                 const LAS unsigned char* kb = lds + F_KB0 + buf * F_KBS + g * 16 + prow * KSTR;
;                 __builtin_amdgcn_s_setprio(1);
; #pragma unroll
;                 for (int kk = 0; kk < DK / 16; ++kk) {
;                     const bf16x8 a0 = *(const LAS bf16x8*)(kb + kk * 32);
;                     const bf16x8 a1 = *(const LAS bf16x8*)(kb + 32 * KSTR + kk * 32);
;                     s0 = mfma32(a0, qf[kk], s0); s1 = mfma32(a1, qf[kk], s1);
;                 }
;                 __builtin_amdgcn_s_setprio(0);
;                 const bool need_causal = pos_max > t_wmin;
;                 const bool need_bias = (MODE != M_FOX) && ((t_wmin - pos_max) < 128);
;                 const bool need_win = (MODE == M_WIN) && (t_wmax - pos_min >= 512);
;                 if (!PASS2 && !(need_causal || need_bias || need_win)) {
;                     float mx = fmaxf(s0[0], s1[0]);
; #pragma unroll
;                     for (int r = 1; r < 16; ++r) mx = fmax3(mx, s0[r], s1[r]);
;                     if (MODE == M_SLC) mx = selbit ? mx : NEG;
;                     mx = xhalf_max(mx);
;                     const float mxs = mx * sl2;
;                     const float mn = (mxs > m_run + 8.0f) ? mxs : m_run;
;                     const float alpha = fexp2(m_run - mn);
;                     m_run = mn;
;                     float nm = -mn;
;                     if (MODE == M_SLC) nm = selbit ? nm : -__builtin_inff();
;                     float ps0 = 0.f, ps1 = 0.f;
; #pragma unroll
;                     for (int r = 0; r < 16; ++r) {
;                         s0[r] = fexp2(__builtin_fmaf(s0[r], sl2, nm)); s1[r] = fexp2(__builtin_fmaf(s1[r], sl2, nm));
.LBB0_2269:
	s_mul_i32 s4, s39, 0x4400
	v_add_u32_e32 v2, s4, v243
	s_setprio 1
	ds_read_b128 v[4:7], v2
	ds_read_b128 v[8:11], v2 offset:32
	s_waitcnt lgkmcnt(1)
	v_mfma_f32_32x32x16_bf16 v[82:97], v[4:7], v[114:117], 0
	ds_read_b128 v[4:7], v2 offset:8704
	ds_read_b128 v[12:15], v2 offset:8736
	s_waitcnt lgkmcnt(1)
	v_mfma_f32_32x32x16_bf16 v[98:113], v[4:7], v[114:117], 0
	v_mfma_f32_32x32x16_bf16 v[82:97], v[8:11], v[118:121], v[82:97]
	ds_read_b128 v[4:7], v2 offset:64
	ds_read_b128 v[8:11], v2 offset:96
	s_waitcnt lgkmcnt(2)
	v_mfma_f32_32x32x16_bf16 v[98:113], v[12:15], v[118:121], v[98:113]
	s_waitcnt lgkmcnt(1)
	v_mfma_f32_32x32x16_bf16 v[82:97], v[4:7], v[122:125], v[82:97]
	ds_read_b128 v[4:7], v2 offset:8768
	ds_read_b128 v[12:15], v2 offset:8800
	s_waitcnt lgkmcnt(1)
	v_mfma_f32_32x32x16_bf16 v[98:113], v[4:7], v[122:125], v[98:113]
	v_mfma_f32_32x32x16_bf16 v[82:97], v[8:11], v[126:129], v[82:97]
	ds_read_b128 v[4:7], v2 offset:128
	ds_read_b128 v[8:11], v2 offset:160
	s_waitcnt lgkmcnt(2)
	v_mfma_f32_32x32x16_bf16 v[98:113], v[12:15], v[126:129], v[98:113]
	s_waitcnt lgkmcnt(1)
	v_mfma_f32_32x32x16_bf16 v[82:97], v[4:7], v[130:133], v[82:97]
	ds_read_b128 v[4:7], v2 offset:8832
	ds_read_b128 v[12:15], v2 offset:8864
	s_waitcnt lgkmcnt(1)
	v_mfma_f32_32x32x16_bf16 v[98:113], v[4:7], v[130:133], v[98:113]
	v_mfma_f32_32x32x16_bf16 v[82:97], v[8:11], v[134:137], v[82:97]
	ds_read_b128 v[4:7], v2 offset:192
	ds_read_b128 v[8:11], v2 offset:224
	s_waitcnt lgkmcnt(2)
	v_mfma_f32_32x32x16_bf16 v[98:113], v[12:15], v[134:137], v[98:113]
	s_waitcnt lgkmcnt(1)
	v_mfma_f32_32x32x16_bf16 v[82:97], v[4:7], v[138:141], v[82:97]
	ds_read_b128 v[4:7], v2 offset:8896
	ds_read_b128 v[12:15], v2 offset:8928
	s_waitcnt lgkmcnt(1)
	v_mfma_f32_32x32x16_bf16 v[98:113], v[4:7], v[138:141], v[98:113]
	v_mfma_f32_32x32x16_bf16 v[82:97], v[8:11], v[142:145], v[82:97]
	s_waitcnt lgkmcnt(0)
	v_mfma_f32_32x32x16_bf16 v[98:113], v[12:15], v[142:145], v[98:113]
	s_nop 0
	v_cmp_le_i32_e32 vcc, s38, v162
	v_cmp_lt_i32_e64 s[6:7], s55, v242
	v_cmp_gt_i32_e64 s[4:5], s67, v242
	s_and_b64 s[6:7], vcc, s[6:7]
	v_add_f32_e32 v2, 0x41000000, v249
	s_and_saveexec_b64 s[18:19], s[6:7]
	s_xor_b64 s[6:7], exec, s[18:19]
	s_cbranch_execz .LBB0_2273
	s_cmp_eq_u64 s[6:7], 0
	s_cbranch_scc1 .Lfast_cmp1
	s_nop 2
	v_max_f32_e32 v4, v98, v98
	v_max_f32_e32 v5, v82, v82
	v_max_f32_e32 v4, v5, v4
	v_max3_f32 v4, v4, v83, v99
	s_nop 0
	v_max3_f32 v4, v4, v84, v100
	s_nop 0
	v_max3_f32 v4, v4, v85, v101
	s_nop 0
	v_max3_f32 v4, v4, v86, v102
	s_nop 0
	v_max3_f32 v4, v4, v87, v103
	s_nop 0
	v_max3_f32 v4, v4, v88, v104
	s_nop 0
	v_max3_f32 v4, v4, v89, v105
	s_nop 0
	v_max3_f32 v4, v4, v90, v106
	s_nop 0
	v_max3_f32 v4, v4, v91, v107
	s_nop 0
	v_max3_f32 v4, v4, v92, v108
	s_nop 0
	v_max3_f32 v4, v4, v93, v109
	s_nop 0
	v_max3_f32 v4, v4, v94, v110
	s_nop 0
	v_max3_f32 v4, v4, v95, v111
	s_nop 0
	v_max3_f32 v4, v4, v96, v112
	s_nop 0
	v_max3_f32 v4, v4, v97, v113
	s_nop 0
	v_mov_b32_e32 v5, v4
	s_nop 1
	v_permlane32_swap_b32_e32 v4, v5
	v_max_f32_e32 v5, v5, v5
	v_max_f32_e32 v4, v4, v4
	v_max_f32_e32 v4, v4, v5
	v_mul_f32_e32 v4, 0x3e0293ee, v4
	v_cmp_gt_f32_e32 vcc, v4, v2
	s_nop 1
	v_cndmask_b32_e32 v250, v249, v4, vcc
	v_sub_f32_e32 v2, v249, v250
	v_exp_f32_e32 v2, v2
	s_nop 0
	v_cmp_neq_f32_e32 vcc, 1.0, v2
	s_cbranch_vccz .LBB0_2272
	v_pk_mul_f32 v[80:81], v[80:81], v[2:3] op_sel_hi:[1,0]
	v_pk_mul_f32 v[78:79], v[78:79], v[2:3] op_sel_hi:[1,0]
	v_pk_mul_f32 v[76:77], v[76:77], v[2:3] op_sel_hi:[1,0]
	v_pk_mul_f32 v[74:75], v[74:75], v[2:3] op_sel_hi:[1,0]
	v_pk_mul_f32 v[72:73], v[72:73], v[2:3] op_sel_hi:[1,0]
	v_pk_mul_f32 v[70:71], v[70:71], v[2:3] op_sel_hi:[1,0]
	v_pk_mul_f32 v[68:69], v[68:69], v[2:3] op_sel_hi:[1,0]
	v_pk_mul_f32 v[66:67], v[66:67], v[2:3] op_sel_hi:[1,0]
	v_pk_mul_f32 v[64:65], v[64:65], v[2:3] op_sel_hi:[1,0]
	v_pk_mul_f32 v[62:63], v[62:63], v[2:3] op_sel_hi:[1,0]
	v_pk_mul_f32 v[60:61], v[60:61], v[2:3] op_sel_hi:[1,0]
	v_pk_mul_f32 v[58:59], v[58:59], v[2:3] op_sel_hi:[1,0]
	v_pk_mul_f32 v[56:57], v[56:57], v[2:3] op_sel_hi:[1,0]
	v_pk_mul_f32 v[54:55], v[54:55], v[2:3] op_sel_hi:[1,0]
	v_pk_mul_f32 v[52:53], v[52:53], v[2:3] op_sel_hi:[1,0]
	v_pk_mul_f32 v[50:51], v[50:51], v[2:3] op_sel_hi:[1,0]
	v_pk_mul_f32 v[48:49], v[48:49], v[2:3] op_sel_hi:[1,0]
	v_pk_mul_f32 v[46:47], v[46:47], v[2:3] op_sel_hi:[1,0]
	v_pk_mul_f32 v[44:45], v[44:45], v[2:3] op_sel_hi:[1,0]
	v_pk_mul_f32 v[42:43], v[42:43], v[2:3] op_sel_hi:[1,0]
	v_pk_mul_f32 v[40:41], v[40:41], v[2:3] op_sel_hi:[1,0]
	v_pk_mul_f32 v[38:39], v[38:39], v[2:3] op_sel_hi:[1,0]
	v_pk_mul_f32 v[36:37], v[36:37], v[2:3] op_sel_hi:[1,0]
	v_pk_mul_f32 v[34:35], v[34:35], v[2:3] op_sel_hi:[1,0]
	v_pk_mul_f32 v[32:33], v[32:33], v[2:3] op_sel_hi:[1,0]
	v_pk_mul_f32 v[30:31], v[30:31], v[2:3] op_sel_hi:[1,0]
	v_pk_mul_f32 v[28:29], v[28:29], v[2:3] op_sel_hi:[1,0]
	v_pk_mul_f32 v[26:27], v[26:27], v[2:3] op_sel_hi:[1,0]
	v_pk_mul_f32 v[24:25], v[24:25], v[2:3] op_sel_hi:[1,0]
	v_pk_mul_f32 v[22:23], v[22:23], v[2:3] op_sel_hi:[1,0]
	v_pk_mul_f32 v[20:21], v[20:21], v[2:3] op_sel_hi:[1,0]
	v_pk_mul_f32 v[18:19], v[18:19], v[2:3] op_sel_hi:[1,0]

; template <int MODE, int DK, bool PASS2> ...
;     ...
;                     float ps0 = 0.f, ps1 = 0.f;
; #pragma unroll
;                     for (int r = 0; r < 16; ++r) {
;                         s0[r] = fexp2(__builtin_fmaf(s0[r], sl2, nm)); s1[r] = fexp2(__builtin_fmaf(s1[r], sl2, nm));
;                         ps0 += s0[r]; ps1 += s1[r];
;                     }
;                     l_run = l_run * alpha + (ps0 + ps1);
;                     if (__builtin_amdgcn_ballot_w64(alpha != 1.0f) != 0ull) {
; #pragma unroll
;                         for (int db = 0; db < 4; ++db)
; #pragma unroll
;                             for (int r = 0; r < 16; ++r) O[db][r] *= alpha;
;                     }
;                 } else {
; #pragma unroll
;                     for (int r = 0; r < 16; ++r) { s0[r] *= sl2; s1[r] *= sl2; }
;                     if (need_bias || need_causal || need_win) {
; #pragma unroll
;                         for (int i = 0; i < 32; ++i) {
;                             const int s = kv0 + (i >> 3) * 16 + 8 * g + (i & 7);
;                             const int dist = t_lane - ((MODE == M_CMP) ? 16 * s + 31 : s);
;                             float v = (i < 16) ? s0[i & 15] : s1[i & 15];
;                             if (need_bias) { const int di = dist < 0 ? 0 : (dist > 128 ? 128 : dist); v += tb[di]; }
;                             bool msk = dist < 0;
;                             if (MODE == M_WIN) msk = msk || dist >= 512;
;                             if (msk) v = NEG;
;                             if (i < 16) s0[i & 15] = v; else s1[i & 15] = v;
;                             if ((i & 7) == 7) __builtin_amdgcn_sched_barrier(0);
;                         }
;                     }
;                     if (MODE == M_SLC) {
;                         if (!selbit) {
; #pragma unroll
;                             for (int r = 0; r < 16; ++r) { s0[r] = NEG; s1[r] = NEG; }
;                         }
;                     }
;                     if (!PASS2) {
;                         float mx = fmaxf(s0[0], s1[0]);
; #pragma unroll
;                         for (int r = 1; r < 16; ++r) mx = fmax3(mx, s0[r], s1[r]);
;                         mx = xhalf_max(mx);
;                         const float mn = (mx > m_run + 8.0f) ? mx : m_run;
;                         const float alpha = fexp2(m_run - mn);
;                         m_run = mn;
.Lfast_cmp1_norescale:
	v_fma_f32 v12, v82, s34, -v250
	v_fma_f32 v13, v83, s34, -v250
	v_exp_f32_e32 v4, v12
	v_exp_f32_e32 v5, v13
	v_fma_f32 v14, v84, s34, -v250
	v_fma_f32 v15, v85, s34, -v250
	v_exp_f32_e32 v6, v14
	v_exp_f32_e32 v7, v15
	v_add_f32_e32 v16, v4, v5
	v_fma_f32 v12, v86, s34, -v250
	v_fma_f32 v13, v87, s34, -v250
	v_exp_f32_e32 v8, v12
	v_exp_f32_e32 v9, v13
	v_cvt_pk_bf16_f32 v82, v4, v5
	v_add_f32_e32 v16, v16, v6
	v_fma_f32 v14, v88, s34, -v250
	v_add_f32_e32 v16, v16, v7
	v_fma_f32 v15, v89, s34, -v250
	v_exp_f32_e32 v10, v14
	v_exp_f32_e32 v11, v15
	v_cvt_pk_bf16_f32 v83, v6, v7
	v_add_f32_e32 v16, v16, v8
	v_add_f32_e32 v16, v16, v9
	v_cvt_pk_bf16_f32 v84, v8, v9
	v_add_f32_e32 v16, v16, v10
	v_add_f32_e32 v16, v16, v11
	v_cvt_pk_bf16_f32 v85, v10, v11
	v_fma_f32 v12, v90, s34, -v250
	v_fma_f32 v13, v91, s34, -v250
	s_waitcnt lgkmcnt(2)
	v_mfma_f32_32x32x16_bf16 v[66:81], v[204:207], v[82:85], v[66:81]
	v_exp_f32_e32 v4, v12
	v_exp_f32_e32 v5, v13
	v_fma_f32 v14, v92, s34, -v250
	v_fma_f32 v15, v93, s34, -v250
	v_exp_f32_e32 v6, v14
	v_exp_f32_e32 v7, v15
	s_waitcnt lgkmcnt(1)
	v_mfma_f32_32x32x16_bf16 v[50:65], v[208:211], v[82:85], v[50:65]
	ds_read_b128 v[204:207], v216 offset:48640
	v_add_f32_e32 v16, v16, v4
	v_fma_f32 v12, v94, s34, -v250
	v_add_f32_e32 v16, v16, v5
	v_fma_f32 v13, v95, s34, -v250
	v_exp_f32_e32 v8, v12
	v_exp_f32_e32 v9, v13
	s_waitcnt lgkmcnt(1)
	v_mfma_f32_32x32x16_bf16 v[34:49], v[212:215], v[82:85], v[34:49]
	ds_read_b128 v[208:211], v216 offset:34848
	v_cvt_pk_bf16_f32 v90, v4, v5
	v_add_f32_e32 v16, v16, v6
	v_fma_f32 v14, v96, s34, -v250
	v_add_f32_e32 v16, v16, v7
	v_fma_f32 v15, v97, s34, -v250
	v_exp_f32_e32 v10, v14
	s_waitcnt lgkmcnt(1)
	v_mfma_f32_32x32x16_bf16 v[18:33], v[204:207], v[82:85], v[18:33]
	ds_read_b128 v[212:215], v216 offset:39456
	v_exp_f32_e32 v11, v15
	v_cvt_pk_bf16_f32 v91, v6, v7
	v_add_f32_e32 v16, v16, v8
	v_add_f32_e32 v16, v16, v9
	v_cvt_pk_bf16_f32 v92, v8, v9
	v_add_f32_e32 v16, v16, v10
	v_add_f32_e32 v16, v16, v11
	v_cvt_pk_bf16_f32 v93, v10, v11
	v_fma_f32 v12, v98, s34, -v250
	v_fma_f32 v13, v99, s34, -v250
	s_waitcnt lgkmcnt(1)
	v_mfma_f32_32x32x16_bf16 v[66:81], v[208:211], v[90:93], v[66:81]
	ds_read_b128 v[204:207], v216 offset:44064
	v_exp_f32_e32 v4, v12
	v_exp_f32_e32 v5, v13
	v_fma_f32 v14, v100, s34, -v250
	v_fma_f32 v15, v101, s34, -v250
	v_exp_f32_e32 v6, v14
	v_exp_f32_e32 v7, v15
	s_waitcnt lgkmcnt(1)
	v_mfma_f32_32x32x16_bf16 v[50:65], v[212:215], v[90:93], v[50:65]
	ds_read_b128 v[208:211], v216 offset:48672
	v_add_f32_e32 v17, v4, v5
	v_fma_f32 v12, v102, s34, -v250
	v_fma_f32 v13, v103, s34, -v250
	v_exp_f32_e32 v8, v12
	v_exp_f32_e32 v9, v13
	v_cvt_pk_bf16_f32 v98, v4, v5
	s_waitcnt lgkmcnt(1)
	v_mfma_f32_32x32x16_bf16 v[34:49], v[204:207], v[90:93], v[34:49]
	ds_read_b128 v[212:215], v216 offset:34880
	v_add_f32_e32 v17, v17, v6
	v_fma_f32 v14, v104, s34, -v250
	v_add_f32_e32 v17, v17, v7
	v_fma_f32 v15, v105, s34, -v250
	v_exp_f32_e32 v10, v14
	v_exp_f32_e32 v11, v15
	s_waitcnt lgkmcnt(1)
	v_mfma_f32_32x32x16_bf16 v[18:33], v[208:211], v[90:93], v[18:33]
	ds_read_b128 v[204:207], v216 offset:39488
	v_cvt_pk_bf16_f32 v99, v6, v7
	v_add_f32_e32 v17, v17, v8
	v_add_f32_e32 v17, v17, v9
	v_cvt_pk_bf16_f32 v100, v8, v9
	v_add_f32_e32 v17, v17, v10
	v_add_f32_e32 v17, v17, v11
	v_cvt_pk_bf16_f32 v101, v10, v11
	v_fma_f32 v12, v106, s34, -v250
	v_fma_f32 v13, v107, s34, -v250
	s_waitcnt lgkmcnt(1)
	v_mfma_f32_32x32x16_bf16 v[66:81], v[212:215], v[98:101], v[66:81]
	ds_read_b128 v[208:211], v216 offset:44096
	v_exp_f32_e32 v4, v12
	v_exp_f32_e32 v5, v13
	v_fma_f32 v14, v108, s34, -v250
	v_fma_f32 v15, v109, s34, -v250
	v_exp_f32_e32 v6, v14
	v_exp_f32_e32 v7, v15
	s_waitcnt lgkmcnt(1)
	v_mfma_f32_32x32x16_bf16 v[50:65], v[204:207], v[98:101], v[50:65]
	ds_read_b128 v[212:215], v216 offset:48704
	v_add_f32_e32 v17, v17, v4
	v_fma_f32 v12, v110, s34, -v250
	v_add_f32_e32 v17, v17, v5
	v_fma_f32 v13, v111, s34, -v250
	v_exp_f32_e32 v8, v12
	v_exp_f32_e32 v9, v13
	s_waitcnt lgkmcnt(1)
	v_mfma_f32_32x32x16_bf16 v[34:49], v[208:211], v[98:101], v[34:49]
	ds_read_b128 v[204:207], v216 offset:34912
	v_cvt_pk_bf16_f32 v106, v4, v5
	v_add_f32_e32 v17, v17, v6
	v_fma_f32 v14, v112, s34, -v250
	v_add_f32_e32 v17, v17, v7
	v_fma_f32 v15, v113, s34, -v250
	v_exp_f32_e32 v10, v14
	s_waitcnt lgkmcnt(1)
	v_mfma_f32_32x32x16_bf16 v[18:33], v[212:215], v[98:101], v[18:33]
	ds_read_b128 v[208:211], v216 offset:39520
	v_exp_f32_e32 v11, v15
	v_cvt_pk_bf16_f32 v107, v6, v7
	v_add_f32_e32 v17, v17, v8
	v_add_f32_e32 v17, v17, v9
	v_cvt_pk_bf16_f32 v108, v8, v9
	v_add_f32_e32 v17, v17, v10
	v_add_f32_e32 v17, v17, v11
	v_cvt_pk_bf16_f32 v109, v10, v11
	v_add_f32_e32 v251, v16, v17
	s_waitcnt lgkmcnt(1)
	v_mfma_f32_32x32x16_bf16 v[66:81], v[204:207], v[106:109], v[66:81]
	ds_read_b128 v[212:215], v216 offset:44128
	v_fmac_f32_e32 v251, v248, v2
	s_waitcnt lgkmcnt(1)
	v_mfma_f32_32x32x16_bf16 v[50:65], v[208:211], v[106:109], v[50:65]
	ds_read_b128 v[204:207], v216 offset:48736
	s_waitcnt lgkmcnt(1)
	v_mfma_f32_32x32x16_bf16 v[34:49], v[212:215], v[106:109], v[34:49]
	s_waitcnt lgkmcnt(0)
	v_mfma_f32_32x32x16_bf16 v[18:33], v[204:207], v[106:109], v[18:33]
	s_nop 0
	s_branch .Lpostpv_cmp1

; template <int MODE, int DK, bool PASS2> ...
;     ...
;             bool selbit = true;
;             if (MODE == M_SLC) {
;                 selbit = ((((const LAS unsigned*)impw)[j >> 5] >> (j & 31)) & 1u) != 0u;
;                 active = active && (__builtin_amdgcn_ballot_w64(selbit) != 0ull);
;             }
;             if (active) {
;                 f32x16 s0, s1;
;                 if (MODE == M_FOX) {
;                     const LAS float* ct = (const LAS float*)(lds + F_CT + buf * 256) + 8 * g;
; #pragma unroll
;                     for (int q4 = 0; q4 < 4; ++q4) {
;                         const f32x4 a = *(const LAS f32x4*)(ct + (q4 >> 1) * 16 + (q4 & 1) * 4), b = *(const LAS f32x4*)(ct + 32 + (q4 >> 1) * 16 + (q4 & 1) * 4);
; #pragma unroll
;                         for (int e = 0; e < 4; ++e) { s0[q4 * 4 + e] = a[e]; s1[q4 * 4 + e] = b[e]; }
;                     }
;                 } else { s0 = (f32x16)(0.f); s1 = (f32x16)(0.f); }
;                 const LAS unsigned char* kb = lds + F_KB0 + buf * F_KBS + g * 16 + prow * KSTR;
;                 __builtin_amdgcn_s_setprio(1);
; #pragma unroll
;                 for (int kk = 0; kk < DK / 16; ++kk) {
;                     const bf16x8 a0 = *(const LAS bf16x8*)(kb + kk * 32);
;                     const bf16x8 a1 = *(const LAS bf16x8*)(kb + 32 * KSTR + kk * 32);
;                     s0 = mfma32(a0, qf[kk], s0); s1 = mfma32(a1, qf[kk], s1);
;                 }
;                 __builtin_amdgcn_s_setprio(0);
;                 const bool need_causal = pos_max > t_wmin;
;                 const bool need_bias = (MODE != M_FOX) && ((t_wmin - pos_max) < 128);
;                 const bool need_win = (MODE == M_WIN) && (t_wmax - pos_min >= 512);
;                 if (!PASS2 && !(need_causal || need_bias || need_win)) {
;                     float mx = fmaxf(s0[0], s1[0]);
; #pragma unroll
;                     for (int r = 1; r < 16; ++r) mx = fmax3(mx, s0[r], s1[r]);
;                     if (MODE == M_SLC) mx = selbit ? mx : NEG;
;                     mx = xhalf_max(mx);
;                     const float mxs = mx * sl2;
;                     const float mn = (mxs > m_run + 8.0f) ? mxs : m_run;
;                     const float alpha = fexp2(m_run - mn);
;                     m_run = mn;
;                     float nm = -mn;
;                     if (MODE == M_SLC) nm = selbit ? nm : -__builtin_inff();
.Lslc_selhit:
	s_and_b32 s4, s48, 31
	v_lshrrev_b32_e32 v4, s48, v246
	v_bfe_u32 v2, v246, s4, 1
	v_and_b32_e32 v4, 1, v4
	v_cmp_ne_u32_e32 vcc, 0, v2
	v_cmp_eq_u32_e64 s[4:5], 1, v4
	s_cbranch_vccz .LBB0_2610
	s_mul_i32 s6, s74, 0x4400
	s_or_b32 s48, s78, 63
	v_add_u32_e32 v2, s6, v215
	s_setprio 1
	ds_read_b128 v[4:7], v2
	ds_read_b128 v[8:11], v2 offset:32
	s_waitcnt lgkmcnt(1)
	v_mfma_f32_32x32x16_bf16 v[98:113], v[4:7], v[114:117], 0
	ds_read_b128 v[4:7], v2 offset:8704
	ds_read_b128 v[12:15], v2 offset:8736
	s_waitcnt lgkmcnt(1)
	v_mfma_f32_32x32x16_bf16 v[82:97], v[4:7], v[114:117], 0
	v_mfma_f32_32x32x16_bf16 v[98:113], v[8:11], v[118:121], v[98:113]
	ds_read_b128 v[4:7], v2 offset:64
	ds_read_b128 v[8:11], v2 offset:96
	s_waitcnt lgkmcnt(2)
	v_mfma_f32_32x32x16_bf16 v[82:97], v[12:15], v[118:121], v[82:97]
	s_waitcnt lgkmcnt(1)
	v_mfma_f32_32x32x16_bf16 v[98:113], v[4:7], v[122:125], v[98:113]
	ds_read_b128 v[4:7], v2 offset:8768
	ds_read_b128 v[12:15], v2 offset:8800
	s_waitcnt lgkmcnt(1)
	v_mfma_f32_32x32x16_bf16 v[82:97], v[4:7], v[122:125], v[82:97]
	v_mfma_f32_32x32x16_bf16 v[98:113], v[8:11], v[126:129], v[98:113]
	ds_read_b128 v[4:7], v2 offset:128
	ds_read_b128 v[8:11], v2 offset:160
	s_waitcnt lgkmcnt(2)
	v_mfma_f32_32x32x16_bf16 v[82:97], v[12:15], v[126:129], v[82:97]
	s_waitcnt lgkmcnt(1)
	v_mfma_f32_32x32x16_bf16 v[98:113], v[4:7], v[130:133], v[98:113]
	ds_read_b128 v[4:7], v2 offset:8832
	ds_read_b128 v[12:15], v2 offset:8864
	s_waitcnt lgkmcnt(1)
	v_mfma_f32_32x32x16_bf16 v[82:97], v[4:7], v[130:133], v[82:97]
	v_mfma_f32_32x32x16_bf16 v[98:113], v[8:11], v[134:137], v[98:113]
	ds_read_b128 v[4:7], v2 offset:192
	ds_read_b128 v[8:11], v2 offset:224
	s_waitcnt lgkmcnt(2)
	v_mfma_f32_32x32x16_bf16 v[82:97], v[12:15], v[134:137], v[82:97]
	s_waitcnt lgkmcnt(1)
	v_mfma_f32_32x32x16_bf16 v[98:113], v[4:7], v[138:141], v[98:113]
	ds_read_b128 v[4:7], v2 offset:8896
	ds_read_b128 v[12:15], v2 offset:8928
	s_waitcnt lgkmcnt(1)
	v_mfma_f32_32x32x16_bf16 v[82:97], v[4:7], v[138:141], v[82:97]
	v_mfma_f32_32x32x16_bf16 v[98:113], v[8:11], v[142:145], v[98:113]
	s_waitcnt lgkmcnt(0)
	v_mfma_f32_32x32x16_bf16 v[82:97], v[12:15], v[142:145], v[82:97]
	s_nop 0
	v_min_i32_e32 v2, v199, v207
	v_cmp_gt_i32_e64 s[6:7], s48, v207
	v_cmp_le_i32_e32 vcc, s48, v2
	v_add_f32_e32 v2, 0x41000000, v217
	s_and_saveexec_b64 s[48:49], vcc
	s_xor_b64 s[48:49], exec, s[48:49]
	s_cbranch_execz .LBB0_2603
	s_cmp_eq_u64 s[48:49], 0
	s_cbranch_scc1 .Lfast_slc
	s_nop 3
	v_max_f32_e32 v4, v82, v82
	v_max_f32_e32 v5, v98, v98
	v_max_f32_e32 v4, v5, v4
	v_max3_f32 v4, v4, v99, v83
	s_nop 0
	v_max3_f32 v4, v4, v100, v84
	s_nop 0
	v_max3_f32 v4, v4, v101, v85
	s_nop 0
	v_max3_f32 v4, v4, v102, v86
	s_nop 0
	v_max3_f32 v4, v4, v103, v87
	s_nop 0
	v_max3_f32 v4, v4, v104, v88
	s_nop 0
	v_max3_f32 v4, v4, v105, v89
	s_nop 0
	v_max3_f32 v4, v4, v106, v90
	s_nop 0
	v_max3_f32 v4, v4, v107, v91
	s_nop 0
	v_max3_f32 v4, v4, v108, v92
	s_nop 0
	v_max3_f32 v4, v4, v109, v93
	s_nop 0
	v_max3_f32 v4, v4, v110, v94
	s_nop 0
	v_max3_f32 v4, v4, v111, v95
	s_nop 0
	v_max3_f32 v4, v4, v112, v96
	s_nop 0
	v_max3_f32 v4, v4, v113, v97
	s_nop 0
	v_cndmask_b32_e64 v4, v194, v4, s[4:5]
	v_mov_b32_e32 v5, v4
	s_nop 1
	v_permlane32_swap_b32_e32 v4, v5
	v_max_f32_e32 v5, v5, v5
	v_max_f32_e32 v4, v4, v4
	v_max_f32_e32 v4, v4, v5
	v_mul_f32_e32 v4, 0x3e0293ee, v4
	v_cmp_gt_f32_e32 vcc, v4, v2
	s_nop 1
	v_cndmask_b32_e32 v218, v217, v4, vcc
	v_sub_f32_e32 v2, v217, v218
	v_exp_f32_e32 v2, v2
	s_nop 0
	v_cmp_neq_f32_e32 vcc, 1.0, v2
	s_cbranch_vccz .LBB0_2602
	v_pk_mul_f32 v[80:81], v[80:81], v[2:3] op_sel_hi:[1,0]
	v_pk_mul_f32 v[78:79], v[78:79], v[2:3] op_sel_hi:[1,0]
	v_pk_mul_f32 v[76:77], v[76:77], v[2:3] op_sel_hi:[1,0]
	v_pk_mul_f32 v[74:75], v[74:75], v[2:3] op_sel_hi:[1,0]
	v_pk_mul_f32 v[72:73], v[72:73], v[2:3] op_sel_hi:[1,0]
	v_pk_mul_f32 v[70:71], v[70:71], v[2:3] op_sel_hi:[1,0]
	v_pk_mul_f32 v[68:69], v[68:69], v[2:3] op_sel_hi:[1,0]
	v_pk_mul_f32 v[66:67], v[66:67], v[2:3] op_sel_hi:[1,0]
	v_pk_mul_f32 v[64:65], v[64:65], v[2:3] op_sel_hi:[1,0]
	v_pk_mul_f32 v[62:63], v[62:63], v[2:3] op_sel_hi:[1,0]
	v_pk_mul_f32 v[60:61], v[60:61], v[2:3] op_sel_hi:[1,0]
	v_pk_mul_f32 v[58:59], v[58:59], v[2:3] op_sel_hi:[1,0]
	v_pk_mul_f32 v[56:57], v[56:57], v[2:3] op_sel_hi:[1,0]
	v_pk_mul_f32 v[54:55], v[54:55], v[2:3] op_sel_hi:[1,0]
	v_pk_mul_f32 v[52:53], v[52:53], v[2:3] op_sel_hi:[1,0]
	v_pk_mul_f32 v[50:51], v[50:51], v[2:3] op_sel_hi:[1,0]
	v_pk_mul_f32 v[48:49], v[48:49], v[2:3] op_sel_hi:[1,0]
	v_pk_mul_f32 v[46:47], v[46:47], v[2:3] op_sel_hi:[1,0]
	v_pk_mul_f32 v[44:45], v[44:45], v[2:3] op_sel_hi:[1,0]
	v_pk_mul_f32 v[42:43], v[42:43], v[2:3] op_sel_hi:[1,0]
	v_pk_mul_f32 v[40:41], v[40:41], v[2:3] op_sel_hi:[1,0]
	v_pk_mul_f32 v[38:39], v[38:39], v[2:3] op_sel_hi:[1,0]
	v_pk_mul_f32 v[36:37], v[36:37], v[2:3] op_sel_hi:[1,0]
	v_pk_mul_f32 v[34:35], v[34:35], v[2:3] op_sel_hi:[1,0]
	v_pk_mul_f32 v[32:33], v[32:33], v[2:3] op_sel_hi:[1,0]
	v_pk_mul_f32 v[30:31], v[30:31], v[2:3] op_sel_hi:[1,0]
	v_pk_mul_f32 v[28:29], v[28:29], v[2:3] op_sel_hi:[1,0]
	v_pk_mul_f32 v[26:27], v[26:27], v[2:3] op_sel_hi:[1,0]
	v_pk_mul_f32 v[24:25], v[24:25], v[2:3] op_sel_hi:[1,0]
	v_pk_mul_f32 v[22:23], v[22:23], v[2:3] op_sel_hi:[1,0]
	v_pk_mul_f32 v[20:21], v[20:21], v[2:3] op_sel_hi:[1,0]
	v_pk_mul_f32 v[18:19], v[18:19], v[2:3] op_sel_hi:[1,0]

; template <int MODE, int DK, bool PASS2> ...
;     ...
;                     if (MODE == M_SLC) nm = selbit ? nm : -__builtin_inff();
;                     float ps0 = 0.f, ps1 = 0.f;
; #pragma unroll
;                     for (int r = 0; r < 16; ++r) {
;                         s0[r] = fexp2(__builtin_fmaf(s0[r], sl2, nm)); s1[r] = fexp2(__builtin_fmaf(s1[r], sl2, nm));
;                         ps0 += s0[r]; ps1 += s1[r];
;                     }
;                     l_run = l_run * alpha + (ps0 + ps1);
;                     if (__builtin_amdgcn_ballot_w64(alpha != 1.0f) != 0ull) {
; #pragma unroll
;                         for (int db = 0; db < 4; ++db)
; #pragma unroll
;                             for (int r = 0; r < 16; ++r) O[db][r] *= alpha;
;                     }
;                 } else {
; #pragma unroll
;                     for (int r = 0; r < 16; ++r) { s0[r] *= sl2; s1[r] *= sl2; }
;                     if (need_bias || need_causal || need_win) {
; #pragma unroll
;                         for (int i = 0; i < 32; ++i) {
;                             const int s = kv0 + (i >> 3) * 16 + 8 * g + (i & 7);
;                             const int dist = t_lane - ((MODE == M_CMP) ? 16 * s + 31 : s);
;                             float v = (i < 16) ? s0[i & 15] : s1[i & 15];
;                             if (need_bias) { const int di = dist < 0 ? 0 : (dist > 128 ? 128 : dist); v += tb[di]; }
;                             bool msk = dist < 0;
;                             if (MODE == M_WIN) msk = msk || dist >= 512;
;                             if (msk) v = NEG;
;                             if (i < 16) s0[i & 15] = v; else s1[i & 15] = v;
;                             if ((i & 7) == 7) __builtin_amdgcn_sched_barrier(0);
;                         }
;                     }
;                     if (MODE == M_SLC) {
;                         if (!selbit) {
; #pragma unroll
;                             for (int r = 0; r < 16; ++r) { s0[r] = NEG; s1[r] = NEG; }
;                         }
;                     }
;                     if (!PASS2) {
;                         float mx = fmaxf(s0[0], s1[0]);
; #pragma unroll
;                         for (int r = 1; r < 16; ++r) mx = fmax3(mx, s0[r], s1[r]);
;                         mx = xhalf_max(mx);
;                         const float mn = (mx > m_run + 8.0f) ? mx : m_run;
.Lfast_slc_norescale:
	v_cndmask_b32_e64 v191, v195, -v218, s[4:5]
	v_fmamk_f32 v12, v98, 0x3e0293ee, v191
	v_fmamk_f32 v13, v99, 0x3e0293ee, v191
	v_exp_f32_e32 v4, v12
	v_exp_f32_e32 v5, v13
	v_fmamk_f32 v14, v100, 0x3e0293ee, v191
	v_fmamk_f32 v15, v101, 0x3e0293ee, v191
	v_exp_f32_e32 v6, v14
	v_exp_f32_e32 v7, v15
	v_add_f32_e32 v16, v4, v5
	v_fmamk_f32 v12, v102, 0x3e0293ee, v191
	v_fmamk_f32 v13, v103, 0x3e0293ee, v191
	v_exp_f32_e32 v8, v12
	v_exp_f32_e32 v9, v13
	v_cvt_pk_bf16_f32 v98, v4, v5
	v_add_f32_e32 v16, v16, v6
	v_fmamk_f32 v14, v104, 0x3e0293ee, v191
	v_add_f32_e32 v16, v16, v7
	v_fmamk_f32 v15, v105, 0x3e0293ee, v191
	v_exp_f32_e32 v10, v14
	v_exp_f32_e32 v11, v15
	v_cvt_pk_bf16_f32 v99, v6, v7
	v_add_f32_e32 v16, v16, v8
	v_add_f32_e32 v16, v16, v9
	v_cvt_pk_bf16_f32 v100, v8, v9
	v_add_f32_e32 v16, v16, v10
	v_add_f32_e32 v16, v16, v11
	v_cvt_pk_bf16_f32 v101, v10, v11
	v_fmamk_f32 v12, v106, 0x3e0293ee, v191
	v_fmamk_f32 v13, v107, 0x3e0293ee, v191
	s_waitcnt lgkmcnt(5)
	v_mfma_f32_32x32x16_bf16 v[66:81], v[222:225], v[98:101], v[66:81]
	v_exp_f32_e32 v4, v12
	v_exp_f32_e32 v5, v13
	v_fmamk_f32 v14, v108, 0x3e0293ee, v191
	v_fmamk_f32 v15, v109, 0x3e0293ee, v191
	v_exp_f32_e32 v6, v14
	v_exp_f32_e32 v7, v15
	s_waitcnt lgkmcnt(4)
	v_mfma_f32_32x32x16_bf16 v[50:65], v[226:229], v[98:101], v[50:65]
	ds_read_b128 v[222:225], v220 offset:44064
	v_add_f32_e32 v16, v16, v4
	v_fmamk_f32 v12, v110, 0x3e0293ee, v191
	v_add_f32_e32 v16, v16, v5
	v_fmamk_f32 v13, v111, 0x3e0293ee, v191
	v_exp_f32_e32 v8, v12
	v_exp_f32_e32 v9, v13
	s_waitcnt lgkmcnt(4)
	v_mfma_f32_32x32x16_bf16 v[34:49], v[230:233], v[98:101], v[34:49]
	ds_read_b128 v[226:229], v220 offset:48672
	v_cvt_pk_bf16_f32 v106, v4, v5
	v_add_f32_e32 v16, v16, v6
	v_fmamk_f32 v14, v112, 0x3e0293ee, v191
	v_add_f32_e32 v16, v16, v7
	v_fmamk_f32 v15, v113, 0x3e0293ee, v191
	v_exp_f32_e32 v10, v14
	s_waitcnt lgkmcnt(4)
	v_mfma_f32_32x32x16_bf16 v[18:33], v[234:237], v[98:101], v[18:33]
	ds_read_b128 v[230:233], v220 offset:34880
	v_exp_f32_e32 v11, v15
	v_cvt_pk_bf16_f32 v107, v6, v7
	v_add_f32_e32 v16, v16, v8
	v_add_f32_e32 v16, v16, v9
	v_cvt_pk_bf16_f32 v108, v8, v9
	v_add_f32_e32 v16, v16, v10
	v_add_f32_e32 v16, v16, v11
	v_cvt_pk_bf16_f32 v109, v10, v11
	v_fmamk_f32 v12, v82, 0x3e0293ee, v191
	v_fmamk_f32 v13, v83, 0x3e0293ee, v191
	s_waitcnt lgkmcnt(4)
	v_mfma_f32_32x32x16_bf16 v[66:81], v[238:241], v[106:109], v[66:81]
	ds_read_b128 v[234:237], v220 offset:39488
	v_exp_f32_e32 v4, v12
	v_exp_f32_e32 v5, v13
	v_fmamk_f32 v14, v84, 0x3e0293ee, v191
	v_fmamk_f32 v15, v85, 0x3e0293ee, v191
	v_exp_f32_e32 v6, v14
	v_exp_f32_e32 v7, v15
	s_waitcnt lgkmcnt(4)
	v_mfma_f32_32x32x16_bf16 v[50:65], v[242:245], v[106:109], v[50:65]
	ds_read_b128 v[238:241], v220 offset:44096
	v_add_f32_e32 v17, v4, v5
	v_fmamk_f32 v12, v86, 0x3e0293ee, v191
	v_fmamk_f32 v13, v87, 0x3e0293ee, v191
	v_exp_f32_e32 v8, v12
	v_exp_f32_e32 v9, v13
	v_cvt_pk_bf16_f32 v82, v4, v5
	s_waitcnt lgkmcnt(4)
	v_mfma_f32_32x32x16_bf16 v[34:49], v[222:225], v[106:109], v[34:49]
	ds_read_b128 v[242:245], v220 offset:48704
	v_add_f32_e32 v17, v17, v6
	v_fmamk_f32 v14, v88, 0x3e0293ee, v191
	v_add_f32_e32 v17, v17, v7
	v_fmamk_f32 v15, v89, 0x3e0293ee, v191
	v_exp_f32_e32 v10, v14
	v_exp_f32_e32 v11, v15
	s_waitcnt lgkmcnt(4)
	v_mfma_f32_32x32x16_bf16 v[18:33], v[226:229], v[106:109], v[18:33]
	ds_read_b128 v[222:225], v220 offset:34912
	v_cvt_pk_bf16_f32 v83, v6, v7
	v_add_f32_e32 v17, v17, v8
	v_add_f32_e32 v17, v17, v9
	v_cvt_pk_bf16_f32 v84, v8, v9
	v_add_f32_e32 v17, v17, v10
	v_add_f32_e32 v17, v17, v11
	v_cvt_pk_bf16_f32 v85, v10, v11
	v_fmamk_f32 v12, v90, 0x3e0293ee, v191
	v_fmamk_f32 v13, v91, 0x3e0293ee, v191
	s_waitcnt lgkmcnt(4)
	v_mfma_f32_32x32x16_bf16 v[66:81], v[230:233], v[82:85], v[66:81]
	ds_read_b128 v[226:229], v220 offset:39520
	v_exp_f32_e32 v4, v12
	v_exp_f32_e32 v5, v13
	v_fmamk_f32 v14, v92, 0x3e0293ee, v191
	v_fmamk_f32 v15, v93, 0x3e0293ee, v191
	v_exp_f32_e32 v6, v14
	v_exp_f32_e32 v7, v15
	s_waitcnt lgkmcnt(4)
	v_mfma_f32_32x32x16_bf16 v[50:65], v[234:237], v[82:85], v[50:65]
	ds_read_b128 v[230:233], v220 offset:44128
	v_add_f32_e32 v17, v17, v4
	v_fmamk_f32 v12, v94, 0x3e0293ee, v191
	v_add_f32_e32 v17, v17, v5
	v_fmamk_f32 v13, v95, 0x3e0293ee, v191
	v_exp_f32_e32 v8, v12
	v_exp_f32_e32 v9, v13
	s_waitcnt lgkmcnt(4)
	v_mfma_f32_32x32x16_bf16 v[34:49], v[238:241], v[82:85], v[34:49]
	ds_read_b128 v[234:237], v220 offset:48736
	v_cvt_pk_bf16_f32 v90, v4, v5
	v_add_f32_e32 v17, v17, v6
	v_fmamk_f32 v14, v96, 0x3e0293ee, v191
	v_add_f32_e32 v17, v17, v7
	v_fmamk_f32 v15, v97, 0x3e0293ee, v191
	v_exp_f32_e32 v10, v14
	s_waitcnt lgkmcnt(4)
	v_mfma_f32_32x32x16_bf16 v[18:33], v[242:245], v[82:85], v[18:33]
	v_exp_f32_e32 v11, v15
	v_cvt_pk_bf16_f32 v91, v6, v7
	v_add_f32_e32 v17, v17, v8
	v_add_f32_e32 v17, v17, v9
	v_cvt_pk_bf16_f32 v92, v8, v9
	v_add_f32_e32 v17, v17, v10
	v_add_f32_e32 v17, v17, v11
	v_cvt_pk_bf16_f32 v93, v10, v11
	v_add_f32_e32 v219, v16, v17
	s_waitcnt lgkmcnt(3)
	v_mfma_f32_32x32x16_bf16 v[66:81], v[222:225], v[90:93], v[66:81]
	v_fmac_f32_e32 v219, v216, v2
	s_waitcnt lgkmcnt(2)
	v_mfma_f32_32x32x16_bf16 v[50:65], v[226:229], v[90:93], v[50:65]
	s_waitcnt lgkmcnt(1)
	v_mfma_f32_32x32x16_bf16 v[34:49], v[230:233], v[90:93], v[34:49]
	s_waitcnt lgkmcnt(0)
	v_mfma_f32_32x32x16_bf16 v[18:33], v[234:237], v[90:93], v[18:33]
	s_nop 0
	s_branch .Lpostpv_slc
